# K loops loop-edge: pointer/counter increments moved from the post-MFMA tail into the last phase's load segment (as m0-write fillers), shortening the tail before the closing barrier
# speedup vs baseline: 1.0057x; 1.0004x over previous
.LBB0_118:
	ds_read_b128 v[128:131], v221
	ds_read_b128 v[132:135], v221 offset:1024
	ds_read_b128 v[136:139], v221 offset:2048
	ds_read_b128 v[140:143], v221 offset:3072
	s_add_u32 s8, s6, 0xfff80080
	s_addc_u32 s9, s7, -1
	s_cmp_eq_u32 s53, 28
	s_cselect_b32 s11, s5, s9
	s_cselect_b32 s10, s33, s8
	s_cselect_b32 s9, s43, s52
	s_cselect_b32 s8, s45, s51

	s_add_i32 m0, s58, 0xc000
	ds_read_b128 v[144:147], v222
	ds_read_b128 v[148:151], v222 offset:1024
	ds_read_b128 v[152:155], v222 offset:2048
	ds_read_b128 v[156:159], v222 offset:3072
	ds_read_b128 v[160:163], v222 offset:4096
	ds_read_b128 v[164:167], v222 offset:5120
	ds_read_b128 v[190:193], v222 offset:6144
	ds_read_b128 v[194:197], v222 offset:7168
	global_load_lds_dwordx4 v182, s[6:7]
	s_add_i32 m0, s58, 0xe000
	s_nop 0

	global_load_lds_dwordx4 v184, s[6:7]
	s_waitcnt lgkmcnt(8)
	s_barrier
	s_waitcnt lgkmcnt(0)


	v_mfma_f32_16x16x32_bf16 v[124:127], v[128:131], v[144:147], v[124:127]
	v_mfma_f32_16x16x32_bf16 v[116:119], v[136:139], v[144:147], v[116:119]
	v_mfma_f32_16x16x32_bf16 v[108:111], v[128:131], v[152:155], v[108:111]
	v_mfma_f32_16x16x32_bf16 v[100:103], v[136:139], v[152:155], v[100:103]
	v_mfma_f32_16x16x32_bf16 v[92:95], v[128:131], v[160:163], v[92:95]
	v_mfma_f32_16x16x32_bf16 v[84:87], v[136:139], v[160:163], v[84:87]
	v_mfma_f32_16x16x32_bf16 v[76:79], v[128:131], v[190:193], v[76:79]
	v_mfma_f32_16x16x32_bf16 v[68:71], v[136:139], v[190:193], v[68:71]
	v_mfma_f32_16x16x32_bf16 v[124:127], v[132:135], v[148:151], v[124:127]
	v_mfma_f32_16x16x32_bf16 v[116:119], v[140:143], v[148:151], v[116:119]
	v_mfma_f32_16x16x32_bf16 v[108:111], v[132:135], v[156:159], v[108:111]
	v_mfma_f32_16x16x32_bf16 v[100:103], v[140:143], v[156:159], v[100:103]
	v_mfma_f32_16x16x32_bf16 v[92:95], v[132:135], v[164:167], v[92:95]
	v_mfma_f32_16x16x32_bf16 v[84:87], v[140:143], v[164:167], v[84:87]
	v_mfma_f32_16x16x32_bf16 v[76:79], v[132:135], v[194:197], v[76:79]
	v_mfma_f32_16x16x32_bf16 v[68:71], v[140:143], v[194:197], v[68:71]

	s_barrier
	s_add_i32 s54, s81, s57
	s_add_u32 s66, s8, s20
	s_addc_u32 s67, s9, s21
	s_mov_b32 m0, s54
	ds_read_b128 v[198:201], v223
	ds_read_b128 v[202:205], v223 offset:1024
	ds_read_b128 v[206:209], v223 offset:2048
	ds_read_b128 v[226:229], v223 offset:3072
	global_load_lds_dwordx4 v172, s[8:9]
	s_add_i32 m0, s54, 0x2000
	s_nop 0

	global_load_lds_dwordx4 v174, s[8:9]
	s_barrier
	s_waitcnt lgkmcnt(0)


	v_mfma_f32_16x16x32_bf16 v[120:123], v[198:201], v[144:147], v[120:123]
	v_mfma_f32_16x16x32_bf16 v[112:115], v[206:209], v[144:147], v[112:115]
	v_mfma_f32_16x16x32_bf16 v[104:107], v[198:201], v[152:155], v[104:107]
	v_mfma_f32_16x16x32_bf16 v[96:99], v[206:209], v[152:155], v[96:99]
	v_mfma_f32_16x16x32_bf16 v[88:91], v[198:201], v[160:163], v[88:91]
	v_mfma_f32_16x16x32_bf16 v[80:83], v[206:209], v[160:163], v[80:83]
	v_mfma_f32_16x16x32_bf16 v[72:75], v[198:201], v[190:193], v[72:75]
	v_mfma_f32_16x16x32_bf16 v[64:67], v[206:209], v[190:193], v[64:67]
	v_mfma_f32_16x16x32_bf16 v[120:123], v[202:205], v[148:151], v[120:123]
	v_mfma_f32_16x16x32_bf16 v[112:115], v[226:229], v[148:151], v[112:115]
	v_mfma_f32_16x16x32_bf16 v[104:107], v[202:205], v[156:159], v[104:107]
	v_mfma_f32_16x16x32_bf16 v[96:99], v[226:229], v[156:159], v[96:99]
	v_mfma_f32_16x16x32_bf16 v[88:91], v[202:205], v[164:167], v[88:91]
	v_mfma_f32_16x16x32_bf16 v[80:83], v[226:229], v[164:167], v[80:83]
	v_mfma_f32_16x16x32_bf16 v[72:75], v[202:205], v[194:197], v[72:75]
	v_mfma_f32_16x16x32_bf16 v[64:67], v[226:229], v[194:197], v[64:67]

	s_mov_b32 m0, s58
	s_add_u32 s68, s10, s20
	s_addc_u32 s69, s11, s21
	s_barrier
	ds_read_b128 v[144:147], v222 offset:16384
	ds_read_b128 v[148:151], v222 offset:17408
	ds_read_b128 v[152:155], v222 offset:18432
	ds_read_b128 v[156:159], v222 offset:19456
	ds_read_b128 v[160:163], v222 offset:20480
	ds_read_b128 v[164:167], v222 offset:21504
	ds_read_b128 v[190:193], v222 offset:22528
	ds_read_b128 v[194:197], v222 offset:23552
	global_load_lds_dwordx4 v172, s[10:11]
	s_mov_b32 m0, s59
	s_nop 0

	global_load_lds_dwordx4 v174, s[10:11]
	s_barrier
	s_waitcnt lgkmcnt(0)


	v_mfma_f32_16x16x32_bf16 v[60:63], v[128:131], v[144:147], v[60:63]
	v_mfma_f32_16x16x32_bf16 v[52:55], v[136:139], v[144:147], v[52:55]
	v_mfma_f32_16x16x32_bf16 v[44:47], v[128:131], v[152:155], v[44:47]
	v_mfma_f32_16x16x32_bf16 v[36:39], v[136:139], v[152:155], v[36:39]
	v_mfma_f32_16x16x32_bf16 v[28:31], v[128:131], v[160:163], v[28:31]
	v_mfma_f32_16x16x32_bf16 v[20:23], v[136:139], v[160:163], v[20:23]
	v_mfma_f32_16x16x32_bf16 v[12:15], v[128:131], v[190:193], v[12:15]
	v_mfma_f32_16x16x32_bf16 v[4:7], v[136:139], v[190:193], v[4:7]
	v_mfma_f32_16x16x32_bf16 v[60:63], v[132:135], v[148:151], v[60:63]
	v_mfma_f32_16x16x32_bf16 v[52:55], v[140:143], v[148:151], v[52:55]
	v_mfma_f32_16x16x32_bf16 v[44:47], v[132:135], v[156:159], v[44:47]
	v_mfma_f32_16x16x32_bf16 v[36:39], v[140:143], v[156:159], v[36:39]
	v_mfma_f32_16x16x32_bf16 v[28:31], v[132:135], v[164:167], v[28:31]
	v_mfma_f32_16x16x32_bf16 v[20:23], v[140:143], v[164:167], v[20:23]
	v_mfma_f32_16x16x32_bf16 v[12:15], v[132:135], v[194:197], v[12:15]
	v_mfma_f32_16x16x32_bf16 v[4:7], v[140:143], v[194:197], v[4:7]

	s_barrier
	s_add_u32 s54, s8, 0x80000
	s_addc_u32 s55, s9, 0
	s_add_i32 vcc_lo, s30, s57
	s_mov_b32 m0, vcc_lo
	s_nop 0

	global_load_lds_dwordx4 v172, s[54:55]
	s_add_i32 m0, vcc_lo, 0x2000
	s_nop 0

	global_load_lds_dwordx4 v174, s[54:55]
	s_waitcnt vmcnt(6)
	s_barrier

	v_mfma_f32_16x16x32_bf16 v[56:59], v[198:201], v[144:147], v[56:59]
	v_mfma_f32_16x16x32_bf16 v[48:51], v[206:209], v[144:147], v[48:51]
	v_mfma_f32_16x16x32_bf16 v[40:43], v[198:201], v[152:155], v[40:43]
	v_mfma_f32_16x16x32_bf16 v[32:35], v[206:209], v[152:155], v[32:35]
	v_mfma_f32_16x16x32_bf16 v[24:27], v[198:201], v[160:163], v[24:27]
	v_mfma_f32_16x16x32_bf16 v[16:19], v[206:209], v[160:163], v[16:19]
	v_mfma_f32_16x16x32_bf16 v[8:11], v[198:201], v[190:193], v[8:11]
	v_mfma_f32_16x16x32_bf16 v[0:3], v[206:209], v[190:193], v[0:3]
	v_mfma_f32_16x16x32_bf16 v[56:59], v[202:205], v[148:151], v[56:59]
	v_mfma_f32_16x16x32_bf16 v[48:51], v[226:229], v[148:151], v[48:51]
	v_mfma_f32_16x16x32_bf16 v[40:43], v[202:205], v[156:159], v[40:43]
	v_mfma_f32_16x16x32_bf16 v[32:35], v[226:229], v[156:159], v[32:35]
	v_mfma_f32_16x16x32_bf16 v[24:27], v[202:205], v[164:167], v[24:27]
	v_mfma_f32_16x16x32_bf16 v[16:19], v[226:229], v[164:167], v[16:19]
	v_mfma_f32_16x16x32_bf16 v[8:11], v[202:205], v[194:197], v[8:11]
	v_mfma_f32_16x16x32_bf16 v[0:3], v[226:229], v[194:197], v[0:3]

	s_add_i32 s54, 0, 0x18000

	s_barrier
	ds_read_b128 v[128:131], v221 offset:32768
	ds_read_b128 v[132:135], v221 offset:33792
	ds_read_b128 v[136:139], v221 offset:34816
	ds_read_b128 v[140:143], v221 offset:35840
	s_add_u32 s10, s10, 0x80000
	s_addc_u32 s11, s11, 0
	s_mov_b32 m0, s2

	ds_read_b128 v[144:147], v222 offset:32768
	ds_read_b128 v[148:151], v222 offset:33792
	ds_read_b128 v[152:155], v222 offset:34816
	ds_read_b128 v[156:159], v222 offset:35840
	ds_read_b128 v[160:163], v222 offset:36864
	ds_read_b128 v[164:167], v222 offset:37888
	ds_read_b128 v[190:193], v222 offset:38912
	ds_read_b128 v[194:197], v222 offset:39936
	global_load_lds_dwordx4 v172, s[10:11]
	s_mov_b32 m0, s3
	s_nop 0

	global_load_lds_dwordx4 v174, s[10:11]
	s_waitcnt lgkmcnt(8)
	s_barrier
	s_waitcnt lgkmcnt(0)


	v_mfma_f32_16x16x32_bf16 v[124:127], v[128:131], v[144:147], v[124:127]
	v_mfma_f32_16x16x32_bf16 v[116:119], v[136:139], v[144:147], v[116:119]
	v_mfma_f32_16x16x32_bf16 v[108:111], v[128:131], v[152:155], v[108:111]
	v_mfma_f32_16x16x32_bf16 v[100:103], v[136:139], v[152:155], v[100:103]
	v_mfma_f32_16x16x32_bf16 v[92:95], v[128:131], v[160:163], v[92:95]
	v_mfma_f32_16x16x32_bf16 v[84:87], v[136:139], v[160:163], v[84:87]
	v_mfma_f32_16x16x32_bf16 v[76:79], v[128:131], v[190:193], v[76:79]
	v_mfma_f32_16x16x32_bf16 v[68:71], v[136:139], v[190:193], v[68:71]
	v_mfma_f32_16x16x32_bf16 v[124:127], v[132:135], v[148:151], v[124:127]
	v_mfma_f32_16x16x32_bf16 v[116:119], v[140:143], v[148:151], v[116:119]
	v_mfma_f32_16x16x32_bf16 v[108:111], v[132:135], v[156:159], v[108:111]
	v_mfma_f32_16x16x32_bf16 v[100:103], v[140:143], v[156:159], v[100:103]
	v_mfma_f32_16x16x32_bf16 v[92:95], v[132:135], v[164:167], v[92:95]
	v_mfma_f32_16x16x32_bf16 v[84:87], v[140:143], v[164:167], v[84:87]
	v_mfma_f32_16x16x32_bf16 v[76:79], v[132:135], v[194:197], v[76:79]
	v_mfma_f32_16x16x32_bf16 v[68:71], v[140:143], v[194:197], v[68:71]

	s_barrier
	s_add_i32 s10, 0, 0x1c000
	s_add_i32 s11, s54, s57


	s_mov_b32 m0, s11
	ds_read_b128 v[198:201], v223 offset:32768
	ds_read_b128 v[202:205], v223 offset:33792
	ds_read_b128 v[206:209], v223 offset:34816
	ds_read_b128 v[226:229], v223 offset:35840
	global_load_lds_dwordx4 v172, s[66:67]
	s_add_i32 m0, s11, 0x2000
	s_nop 0

	global_load_lds_dwordx4 v174, s[66:67]
	s_barrier
	s_waitcnt lgkmcnt(0)


	v_mfma_f32_16x16x32_bf16 v[120:123], v[198:201], v[144:147], v[120:123]
	v_mfma_f32_16x16x32_bf16 v[112:115], v[206:209], v[144:147], v[112:115]
	v_mfma_f32_16x16x32_bf16 v[104:107], v[198:201], v[152:155], v[104:107]
	v_mfma_f32_16x16x32_bf16 v[96:99], v[206:209], v[152:155], v[96:99]
	v_mfma_f32_16x16x32_bf16 v[88:91], v[198:201], v[160:163], v[88:91]
	v_mfma_f32_16x16x32_bf16 v[80:83], v[206:209], v[160:163], v[80:83]
	v_mfma_f32_16x16x32_bf16 v[72:75], v[198:201], v[190:193], v[72:75]
	v_mfma_f32_16x16x32_bf16 v[64:67], v[206:209], v[190:193], v[64:67]
	v_mfma_f32_16x16x32_bf16 v[120:123], v[202:205], v[148:151], v[120:123]
	v_mfma_f32_16x16x32_bf16 v[112:115], v[226:229], v[148:151], v[112:115]
	v_mfma_f32_16x16x32_bf16 v[104:107], v[202:205], v[156:159], v[104:107]
	v_mfma_f32_16x16x32_bf16 v[96:99], v[226:229], v[156:159], v[96:99]
	v_mfma_f32_16x16x32_bf16 v[88:91], v[202:205], v[164:167], v[88:91]
	v_mfma_f32_16x16x32_bf16 v[80:83], v[226:229], v[164:167], v[80:83]
	v_mfma_f32_16x16x32_bf16 v[72:75], v[202:205], v[194:197], v[72:75]
	v_mfma_f32_16x16x32_bf16 v[64:67], v[226:229], v[194:197], v[64:67]

	s_mov_b32 m0, s96

	s_barrier
	ds_read_b128 v[144:147], v222 offset:49152
	ds_read_b128 v[148:151], v222 offset:50176
	ds_read_b128 v[152:155], v222 offset:51200
	ds_read_b128 v[156:159], v222 offset:52224
	ds_read_b128 v[160:163], v222 offset:53248
	ds_read_b128 v[164:167], v222 offset:54272
	ds_read_b128 v[190:193], v222 offset:55296
	ds_read_b128 v[194:197], v222 offset:56320
	global_load_lds_dwordx4 v172, s[68:69]
	s_mov_b32 m0, s97
	s_nop 0

	global_load_lds_dwordx4 v174, s[68:69]
	s_barrier
	s_waitcnt lgkmcnt(0)


	v_mfma_f32_16x16x32_bf16 v[60:63], v[128:131], v[144:147], v[60:63]
	v_mfma_f32_16x16x32_bf16 v[52:55], v[136:139], v[144:147], v[52:55]
	v_mfma_f32_16x16x32_bf16 v[44:47], v[128:131], v[152:155], v[44:47]
	v_mfma_f32_16x16x32_bf16 v[36:39], v[136:139], v[152:155], v[36:39]
	v_mfma_f32_16x16x32_bf16 v[28:31], v[128:131], v[160:163], v[28:31]
	v_mfma_f32_16x16x32_bf16 v[20:23], v[136:139], v[160:163], v[20:23]
	v_mfma_f32_16x16x32_bf16 v[12:15], v[128:131], v[190:193], v[12:15]
	v_mfma_f32_16x16x32_bf16 v[4:7], v[136:139], v[190:193], v[4:7]
	v_mfma_f32_16x16x32_bf16 v[60:63], v[132:135], v[148:151], v[60:63]
	v_mfma_f32_16x16x32_bf16 v[52:55], v[140:143], v[148:151], v[52:55]
	v_mfma_f32_16x16x32_bf16 v[44:47], v[132:135], v[156:159], v[44:47]
	v_mfma_f32_16x16x32_bf16 v[36:39], v[140:143], v[156:159], v[36:39]
	v_mfma_f32_16x16x32_bf16 v[28:31], v[132:135], v[164:167], v[28:31]
	v_mfma_f32_16x16x32_bf16 v[20:23], v[140:143], v[164:167], v[20:23]
	v_mfma_f32_16x16x32_bf16 v[12:15], v[132:135], v[194:197], v[12:15]
	v_mfma_f32_16x16x32_bf16 v[4:7], v[140:143], v[194:197], v[4:7]

	s_barrier
	s_add_u32 s8, s8, 0x80080
	s_addc_u32 s9, s9, 0
	s_add_i32 s10, s10, s57
	s_mov_b32 m0, s10
	s_add_i32 s53, s53, 2

	global_load_lds_dwordx4 v172, s[8:9]
	s_add_i32 m0, s10, 0x2000
	s_add_u32 s6, s6, 0x100
	s_addc_u32 s7, s7, 0

	global_load_lds_dwordx4 v174, s[8:9]
	s_add_u32 s51, s51, 0x100
	s_addc_u32 s52, s52, 0
	s_waitcnt vmcnt(6)
	s_barrier

	v_mfma_f32_16x16x32_bf16 v[56:59], v[198:201], v[144:147], v[56:59]
	v_mfma_f32_16x16x32_bf16 v[48:51], v[206:209], v[144:147], v[48:51]
	v_mfma_f32_16x16x32_bf16 v[40:43], v[198:201], v[152:155], v[40:43]
	v_mfma_f32_16x16x32_bf16 v[32:35], v[206:209], v[152:155], v[32:35]
	v_mfma_f32_16x16x32_bf16 v[24:27], v[198:201], v[160:163], v[24:27]
	v_mfma_f32_16x16x32_bf16 v[16:19], v[206:209], v[160:163], v[16:19]
	v_mfma_f32_16x16x32_bf16 v[8:11], v[198:201], v[190:193], v[8:11]
	v_mfma_f32_16x16x32_bf16 v[0:3], v[206:209], v[190:193], v[0:3]
	v_mfma_f32_16x16x32_bf16 v[56:59], v[202:205], v[148:151], v[56:59]
	v_mfma_f32_16x16x32_bf16 v[48:51], v[226:229], v[148:151], v[48:51]
	v_mfma_f32_16x16x32_bf16 v[40:43], v[202:205], v[156:159], v[40:43]
	v_mfma_f32_16x16x32_bf16 v[32:35], v[226:229], v[156:159], v[32:35]
	v_mfma_f32_16x16x32_bf16 v[24:27], v[202:205], v[164:167], v[24:27]
	v_mfma_f32_16x16x32_bf16 v[16:19], v[226:229], v[164:167], v[16:19]
	v_mfma_f32_16x16x32_bf16 v[8:11], v[202:205], v[194:197], v[8:11]
	v_mfma_f32_16x16x32_bf16 v[0:3], v[226:229], v[194:197], v[0:3]


	s_cmp_gt_u32 s53, 29
	s_barrier
	s_cbranch_scc0 .LBB0_118
	v_mov_b32_e32 v142, v210
	v_mov_b32_e32 v143, v169
	s_lshl_b32 s33, s4, 8
	s_add_i32 s33, s33, s34
	v_lshl_add_u32 v133, v142, 4, v143
	v_ashrrev_i32_e32 v198, 2, v133
	v_and_b32_e32 v192, 3, v143
	v_and_b32_e32 v128, -4, v133
	s_cmp_gt_i32 s4, 30
	v_lshl_add_u32 v226, v192, 6, v128
	v_add_u32_e32 v190, s33, v198
	s_cselect_b64 s[52:53], -1, 0
	s_cmp_gt_i32 s50, 8
	s_mov_b64 s[4:5], -1
	s_cbranch_scc0 .LBB0_419
	s_cmp_lg_u32 s50, 9
	s_cbranch_scc0 .LBB0_225
	s_cmp_gt_u32 s50, 25
	s_cbranch_scc0 .LBB0_127
	v_mul_f32_e32 v130, 0xbfb8aa3b, v120
	v_mul_f32_e32 v131, 0xbfb8aa3b, v121
	v_mul_f32_e32 v132, 0xbfb8aa3b, v122
	v_mul_f32_e32 v134, 0xbfb8aa3b, v123
	v_mul_f32_e32 v135, 0xbfb8aa3b, v112
	v_mul_f32_e32 v136, 0xbfb8aa3b, v113
	v_mul_f32_e32 v137, 0xbfb8aa3b, v114
	v_mul_f32_e32 v138, 0xbfb8aa3b, v115
	v_mul_f32_e32 v139, 0xbfb8aa3b, v104
	v_mul_f32_e32 v140, 0xbfb8aa3b, v105
	v_mul_f32_e32 v141, 0xbfb8aa3b, v106
	v_mul_f32_e32 v144, 0xbfb8aa3b, v107
	v_mul_f32_e32 v145, 0xbfb8aa3b, v96
	v_mul_f32_e32 v146, 0xbfb8aa3b, v97
	v_mul_f32_e32 v147, 0xbfb8aa3b, v98
	v_mul_f32_e32 v148, 0xbfb8aa3b, v99
	v_mul_f32_e32 v149, 0xbfb8aa3b, v88
	v_mul_f32_e32 v150, 0xbfb8aa3b, v89
	v_mul_f32_e32 v151, 0xbfb8aa3b, v90
	v_mul_f32_e32 v152, 0xbfb8aa3b, v91
	v_mul_f32_e32 v153, 0xbfb8aa3b, v80
	v_mul_f32_e32 v154, 0xbfb8aa3b, v81
	v_mul_f32_e32 v155, 0xbfb8aa3b, v82
	v_mul_f32_e32 v180, 0xbfb8aa3b, v83
	v_mul_f32_e32 v206, 0xbfb8aa3b, v72
	v_mul_f32_e32 v207, 0xbfb8aa3b, v73
	v_mul_f32_e32 v208, 0xbfb8aa3b, v74
	v_mul_f32_e32 v209, 0xbfb8aa3b, v75
	v_mul_f32_e32 v227, 0xbfb8aa3b, v64
	v_mul_f32_e32 v228, 0xbfb8aa3b, v65
	v_mul_f32_e32 v229, 0xbfb8aa3b, v66
	v_mul_f32_e32 v230, 0xbfb8aa3b, v67
	v_exp_f32_e32 v205, v130
	v_exp_f32_e32 v204, v131
	v_exp_f32_e32 v203, v132
	v_exp_f32_e32 v202, v134
	v_exp_f32_e32 v200, v135
	v_exp_f32_e32 v199, v136
	v_exp_f32_e32 v197, v137
	v_exp_f32_e32 v196, v138
	v_exp_f32_e32 v195, v139
	v_exp_f32_e32 v194, v140
	v_exp_f32_e32 v193, v141
	v_exp_f32_e32 v167, v144
	v_exp_f32_e32 v166, v145
	v_exp_f32_e32 v165, v146
	v_exp_f32_e32 v164, v147
	v_exp_f32_e32 v163, v148
	v_exp_f32_e32 v162, v149
	v_exp_f32_e32 v161, v150
	v_exp_f32_e32 v160, v151
	v_exp_f32_e32 v159, v152
	v_exp_f32_e32 v158, v153
	v_exp_f32_e32 v157, v154
	v_exp_f32_e32 v156, v155
	v_exp_f32_e32 v155, v180
	v_exp_f32_e32 v154, v206
	v_exp_f32_e32 v153, v207
	v_exp_f32_e32 v152, v208
	v_exp_f32_e32 v151, v209
	v_exp_f32_e32 v150, v227
	v_exp_f32_e32 v149, v228
	v_exp_f32_e32 v148, v229
	v_exp_f32_e32 v147, v230
	v_ashrrev_i32_e32 v191, 31, v190
	s_cmp_lt_u32 s50, 42
	v_lshlrev_b32_e32 v201, 2, v192
	v_lshlrev_b64 v[128:129], 12, v[190:191]
	v_mul_f32_e32 v146, 0xbfb8aa3b, v56
	v_mul_f32_e32 v145, 0xbfb8aa3b, v57
	v_mul_f32_e32 v144, 0xbfb8aa3b, v58
	v_mul_f32_e32 v141, 0xbfb8aa3b, v59
	v_mul_f32_e32 v140, 0xbfb8aa3b, v48
	v_mul_f32_e32 v139, 0xbfb8aa3b, v49
	v_mul_f32_e32 v138, 0xbfb8aa3b, v50
	v_mul_f32_e32 v137, 0xbfb8aa3b, v51
	v_mul_f32_e32 v136, 0xbfb8aa3b, v40
	v_mul_f32_e32 v135, 0xbfb8aa3b, v41
	v_mul_f32_e32 v134, 0xbfb8aa3b, v42
	v_mul_f32_e32 v132, 0xbfb8aa3b, v43
	s_cbranch_scc1 .LBB0_124
	v_mul_f32_e32 v130, 0xbfb8aa3b, v124
	v_mul_f32_e32 v131, 0xbfb8aa3b, v125
	v_mul_f32_e32 v206, 0xbfb8aa3b, v126
	v_mul_f32_e32 v207, 0xbfb8aa3b, v127
	v_exp_f32_e32 v130, v130
	v_exp_f32_e32 v131, v131
	v_exp_f32_e32 v206, v206
	v_exp_f32_e32 v207, v207
	v_add_f32_e32 v130, 1.0, v130
	v_add_f32_e32 v131, 1.0, v131
	v_add_f32_e32 v206, 1.0, v206
	v_add_f32_e32 v207, 1.0, v207
	v_rcp_f32_e32 v130, v130
	v_rcp_f32_e32 v131, v131
	v_rcp_f32_e32 v206, v206
	v_rcp_f32_e32 v207, v207
	s_lshl_b32 s4, s50, 8
	v_cvt_pk_bf16_f32 v130, v130, v131
	s_add_i32 s4, s28, s4
	v_cvt_pk_bf16_f32 v131, v206, v207
	ds_bpermute_b32 v206, v226, v130
	ds_bpermute_b32 v207, v226, v131
	v_or_b32_e32 v180, s4, v201
	v_lshl_add_u64 v[130:131], s[40:41], 0, v[128:129]
	v_lshlrev_b64 v[208:209], 1, v[180:181]
	v_lshl_add_u64 v[130:131], v[130:131], 0, v[208:209]
	s_waitcnt lgkmcnt(0)
	global_store_dwordx2 v[130:131], v[206:207], off
	v_mul_f32_e32 v180, 0xbfb8aa3b, v116
	v_mul_f32_e32 v206, 0xbfb8aa3b, v117
	v_mul_f32_e32 v207, 0xbfb8aa3b, v118
	v_mul_f32_e32 v208, 0xbfb8aa3b, v119
	v_exp_f32_e32 v180, v180
	v_exp_f32_e32 v206, v206
	v_exp_f32_e32 v207, v207
	v_exp_f32_e32 v208, v208
	v_add_f32_e32 v180, 1.0, v180
	v_add_f32_e32 v206, 1.0, v206
	v_add_f32_e32 v207, 1.0, v207
	v_add_f32_e32 v208, 1.0, v208
	v_rcp_f32_e32 v180, v180
	v_rcp_f32_e32 v206, v206
	v_rcp_f32_e32 v207, v207
	v_rcp_f32_e32 v208, v208
	s_mov_b64 s[4:5], 0x10000
	v_cvt_pk_bf16_f32 v180, v180, v206
	ds_bpermute_b32 v206, v226, v180
	v_cvt_pk_bf16_f32 v207, v207, v208
	ds_bpermute_b32 v207, v226, v207
	v_add_f32_e32 v180, 1.0, v205
	v_add_f32_e32 v208, 1.0, v202
	v_rcp_f32_e32 v180, v180
	v_rcp_f32_e32 v208, v208
	s_waitcnt lgkmcnt(0)
	global_store_dwordx2 v[130:131], v[206:207], off offset:32
	v_add_f32_e32 v206, 1.0, v204
	v_add_f32_e32 v207, 1.0, v203
	v_rcp_f32_e32 v206, v206
	v_rcp_f32_e32 v207, v207
	v_mul_f32_e32 v227, 0xbfb8aa3b, v103
	v_exp_f32_e32 v227, v227
	v_cvt_pk_bf16_f32 v180, v180, v206
	v_cvt_pk_bf16_f32 v207, v207, v208
	ds_bpermute_b32 v206, v226, v180
	ds_bpermute_b32 v207, v226, v207
	v_add_f32_e32 v180, 1.0, v200
	v_add_f32_e32 v208, 1.0, v196
	v_rcp_f32_e32 v180, v180
	v_rcp_f32_e32 v208, v208
	s_waitcnt lgkmcnt(0)
	global_store_dwordx2 v[130:131], v[206:207], off offset:256
	v_add_f32_e32 v206, 1.0, v199
	v_add_f32_e32 v207, 1.0, v197
	v_rcp_f32_e32 v206, v206
	v_rcp_f32_e32 v207, v207
	v_add_f32_e32 v227, 1.0, v227
	v_rcp_f32_e32 v227, v227
	v_cvt_pk_bf16_f32 v180, v180, v206
	v_cvt_pk_bf16_f32 v207, v207, v208
	ds_bpermute_b32 v206, v226, v180
	ds_bpermute_b32 v207, v226, v207
	v_mul_f32_e32 v180, 0xbfb8aa3b, v108
	v_mul_f32_e32 v208, 0xbfb8aa3b, v111
	v_exp_f32_e32 v180, v180
	v_exp_f32_e32 v208, v208
	s_waitcnt lgkmcnt(0)
	global_store_dwordx2 v[130:131], v[206:207], off offset:288
	v_mul_f32_e32 v206, 0xbfb8aa3b, v109
	v_mul_f32_e32 v207, 0xbfb8aa3b, v110
	v_exp_f32_e32 v206, v206
	v_exp_f32_e32 v207, v207
	v_add_f32_e32 v180, 1.0, v180
	v_add_f32_e32 v208, 1.0, v208
	v_add_f32_e32 v206, 1.0, v206
	v_add_f32_e32 v207, 1.0, v207
	v_rcp_f32_e32 v180, v180
	v_rcp_f32_e32 v206, v206
	v_rcp_f32_e32 v207, v207
	v_rcp_f32_e32 v208, v208
	v_cvt_pk_bf16_f32 v180, v180, v206
	ds_bpermute_b32 v206, v226, v180
	v_cvt_pk_bf16_f32 v207, v207, v208
	ds_bpermute_b32 v207, v226, v207
	v_lshl_add_u64 v[208:209], v[130:131], 0, s[4:5]
	s_mov_b32 s4, 0x10000
	v_add_co_u32_e32 v228, vcc, s4, v130
	v_mul_f32_e32 v180, 0xbfb8aa3b, v100
	s_nop 0
	v_addc_co_u32_e32 v229, vcc, 0, v131, vcc
	s_waitcnt lgkmcnt(0)
	global_store_dwordx2 v[228:229], v[206:207], off
	v_mul_f32_e32 v206, 0xbfb8aa3b, v101
	v_mul_f32_e32 v207, 0xbfb8aa3b, v102
	v_exp_f32_e32 v180, v180
	v_exp_f32_e32 v206, v206
	v_exp_f32_e32 v207, v207
	s_mov_b64 s[4:5], 0x20000
	v_add_f32_e32 v180, 1.0, v180
	v_add_f32_e32 v206, 1.0, v206
	v_add_f32_e32 v207, 1.0, v207
	v_rcp_f32_e32 v180, v180
	v_rcp_f32_e32 v206, v206
	v_rcp_f32_e32 v207, v207
	v_cvt_pk_bf16_f32 v180, v180, v206
	v_cvt_pk_bf16_f32 v207, v207, v227
	ds_bpermute_b32 v206, v226, v180
	ds_bpermute_b32 v207, v226, v207
	v_add_f32_e32 v180, 1.0, v195
	v_add_f32_e32 v227, 1.0, v167
	v_rcp_f32_e32 v180, v180
	v_rcp_f32_e32 v227, v227
	s_waitcnt lgkmcnt(0)
	global_store_dwordx2 v[208:209], v[206:207], off offset:32
	v_add_f32_e32 v206, 1.0, v194
	v_add_f32_e32 v207, 1.0, v193
	v_rcp_f32_e32 v206, v206
	v_rcp_f32_e32 v207, v207
	v_cvt_pk_bf16_f32 v180, v180, v206
	v_cvt_pk_bf16_f32 v207, v207, v227
	ds_bpermute_b32 v206, v226, v180
	ds_bpermute_b32 v207, v226, v207
	v_add_f32_e32 v180, 1.0, v166
	v_add_f32_e32 v227, 1.0, v163
	v_rcp_f32_e32 v180, v180
	v_rcp_f32_e32 v227, v227
	s_waitcnt lgkmcnt(0)
	global_store_dwordx2 v[208:209], v[206:207], off offset:256
	v_add_f32_e32 v206, 1.0, v165
	v_add_f32_e32 v207, 1.0, v164
	v_rcp_f32_e32 v206, v206
	v_rcp_f32_e32 v207, v207
	v_cvt_pk_bf16_f32 v180, v180, v206
	v_cvt_pk_bf16_f32 v207, v207, v227
	ds_bpermute_b32 v206, v226, v180
	ds_bpermute_b32 v207, v226, v207
	v_mul_f32_e32 v180, 0xbfb8aa3b, v92
	v_exp_f32_e32 v180, v180
	v_mul_f32_e32 v227, 0xbfb8aa3b, v87
	v_exp_f32_e32 v227, v227
	s_waitcnt lgkmcnt(0)
	global_store_dwordx2 v[208:209], v[206:207], off offset:288
	v_mul_f32_e32 v206, 0xbfb8aa3b, v93
	v_mul_f32_e32 v207, 0xbfb8aa3b, v94
	v_mul_f32_e32 v208, 0xbfb8aa3b, v95
	v_exp_f32_e32 v206, v206
	v_exp_f32_e32 v207, v207
	v_exp_f32_e32 v208, v208
	v_add_f32_e32 v180, 1.0, v180
	v_add_f32_e32 v206, 1.0, v206
	v_add_f32_e32 v207, 1.0, v207
	v_add_f32_e32 v208, 1.0, v208
	v_rcp_f32_e32 v180, v180
	v_rcp_f32_e32 v206, v206
	v_rcp_f32_e32 v207, v207
	v_rcp_f32_e32 v208, v208
	v_add_f32_e32 v227, 1.0, v227
	v_cvt_pk_bf16_f32 v180, v180, v206
	ds_bpermute_b32 v206, v226, v180
	v_cvt_pk_bf16_f32 v207, v207, v208
	ds_bpermute_b32 v207, v226, v207
	v_lshl_add_u64 v[208:209], v[130:131], 0, s[4:5]
	s_mov_b32 s4, 0x20000
	v_add_co_u32_e32 v228, vcc, s4, v130
	v_mul_f32_e32 v180, 0xbfb8aa3b, v84
	s_nop 0
	v_addc_co_u32_e32 v229, vcc, 0, v131, vcc
	s_waitcnt lgkmcnt(0)
	global_store_dwordx2 v[228:229], v[206:207], off
	v_mul_f32_e32 v206, 0xbfb8aa3b, v85
	v_mul_f32_e32 v207, 0xbfb8aa3b, v86
	v_exp_f32_e32 v180, v180
	v_exp_f32_e32 v206, v206
	v_exp_f32_e32 v207, v207
	v_rcp_f32_e32 v227, v227
	v_add_f32_e32 v180, 1.0, v180
	v_add_f32_e32 v206, 1.0, v206
	v_add_f32_e32 v207, 1.0, v207
	v_rcp_f32_e32 v180, v180
	v_rcp_f32_e32 v206, v206
	v_rcp_f32_e32 v207, v207
	s_mov_b64 s[4:5], 0x30000
	v_cvt_pk_bf16_f32 v180, v180, v206
	v_cvt_pk_bf16_f32 v207, v207, v227
	ds_bpermute_b32 v206, v226, v180
	ds_bpermute_b32 v207, v226, v207
	v_add_f32_e32 v180, 1.0, v162
	v_add_f32_e32 v227, 1.0, v159
	v_rcp_f32_e32 v180, v180
	v_rcp_f32_e32 v227, v227
	s_waitcnt lgkmcnt(0)
	global_store_dwordx2 v[208:209], v[206:207], off offset:32
	v_add_f32_e32 v206, 1.0, v161
	v_add_f32_e32 v207, 1.0, v160
	v_rcp_f32_e32 v206, v206
	v_rcp_f32_e32 v207, v207
	v_cvt_pk_bf16_f32 v180, v180, v206
	v_cvt_pk_bf16_f32 v207, v207, v227
	ds_bpermute_b32 v206, v226, v180
	ds_bpermute_b32 v207, v226, v207
	v_add_f32_e32 v180, 1.0, v158
	v_add_f32_e32 v227, 1.0, v155
	v_rcp_f32_e32 v180, v180
	v_rcp_f32_e32 v227, v227
	s_waitcnt lgkmcnt(0)
	global_store_dwordx2 v[208:209], v[206:207], off offset:256
	v_add_f32_e32 v206, 1.0, v157
	v_add_f32_e32 v207, 1.0, v156
	v_rcp_f32_e32 v206, v206
	v_rcp_f32_e32 v207, v207
	v_cvt_pk_bf16_f32 v180, v180, v206
	v_cvt_pk_bf16_f32 v207, v207, v227
	ds_bpermute_b32 v206, v226, v180
	ds_bpermute_b32 v207, v226, v207
	v_mul_f32_e32 v180, 0xbfb8aa3b, v76
	v_exp_f32_e32 v180, v180
	v_mul_f32_e32 v227, 0xbfb8aa3b, v71
	v_exp_f32_e32 v227, v227
	s_waitcnt lgkmcnt(0)
	global_store_dwordx2 v[208:209], v[206:207], off offset:288
	v_mul_f32_e32 v206, 0xbfb8aa3b, v77
	v_mul_f32_e32 v207, 0xbfb8aa3b, v78
	v_mul_f32_e32 v208, 0xbfb8aa3b, v79
	v_exp_f32_e32 v206, v206
	v_exp_f32_e32 v207, v207
	v_exp_f32_e32 v208, v208
	v_add_f32_e32 v180, 1.0, v180
	v_add_f32_e32 v206, 1.0, v206
	v_add_f32_e32 v207, 1.0, v207
	v_add_f32_e32 v208, 1.0, v208
	v_rcp_f32_e32 v180, v180
	v_rcp_f32_e32 v206, v206
	v_rcp_f32_e32 v207, v207
	v_rcp_f32_e32 v208, v208
	v_add_f32_e32 v227, 1.0, v227
	v_cvt_pk_bf16_f32 v180, v180, v206
	ds_bpermute_b32 v206, v226, v180
	v_cvt_pk_bf16_f32 v207, v207, v208
	ds_bpermute_b32 v207, v226, v207
	v_lshl_add_u64 v[208:209], v[130:131], 0, s[4:5]
	s_mov_b32 s4, 0x30000
	v_add_co_u32_e32 v228, vcc, s4, v130
	v_mul_f32_e32 v180, 0xbfb8aa3b, v68
	s_nop 0
	v_addc_co_u32_e32 v229, vcc, 0, v131, vcc
	s_waitcnt lgkmcnt(0)
	global_store_dwordx2 v[228:229], v[206:207], off
	v_mul_f32_e32 v206, 0xbfb8aa3b, v69
	v_mul_f32_e32 v207, 0xbfb8aa3b, v70
	v_exp_f32_e32 v180, v180
	v_exp_f32_e32 v206, v206
	v_exp_f32_e32 v207, v207
	v_rcp_f32_e32 v227, v227
	v_add_f32_e32 v180, 1.0, v180
	v_add_f32_e32 v206, 1.0, v206
	v_add_f32_e32 v207, 1.0, v207
	v_rcp_f32_e32 v180, v180
	v_rcp_f32_e32 v206, v206
	v_rcp_f32_e32 v207, v207
	s_mov_b64 s[4:5], 0x80000
	v_cvt_pk_bf16_f32 v180, v180, v206
	v_cvt_pk_bf16_f32 v207, v207, v227
	ds_bpermute_b32 v206, v226, v180
	ds_bpermute_b32 v207, v226, v207
	v_add_f32_e32 v180, 1.0, v154
	v_add_f32_e32 v227, 1.0, v151
	v_rcp_f32_e32 v180, v180
	v_rcp_f32_e32 v227, v227
	s_waitcnt lgkmcnt(0)
	global_store_dwordx2 v[208:209], v[206:207], off offset:32
	v_add_f32_e32 v206, 1.0, v153
	v_add_f32_e32 v207, 1.0, v152
	v_rcp_f32_e32 v206, v206
	v_rcp_f32_e32 v207, v207
	v_cvt_pk_bf16_f32 v180, v180, v206
	v_cvt_pk_bf16_f32 v207, v207, v227
	ds_bpermute_b32 v206, v226, v180
	ds_bpermute_b32 v207, v226, v207
	v_add_f32_e32 v180, 1.0, v150
	v_add_f32_e32 v227, 1.0, v147
	v_rcp_f32_e32 v180, v180
	v_rcp_f32_e32 v227, v227
	s_waitcnt lgkmcnt(0)
	global_store_dwordx2 v[208:209], v[206:207], off offset:256
	v_add_f32_e32 v206, 1.0, v149
	v_add_f32_e32 v207, 1.0, v148
	v_rcp_f32_e32 v206, v206
	v_rcp_f32_e32 v207, v207
	v_cvt_pk_bf16_f32 v180, v180, v206
	v_cvt_pk_bf16_f32 v207, v207, v227
	ds_bpermute_b32 v206, v226, v180
	ds_bpermute_b32 v207, v226, v207
	v_mul_f32_e32 v180, 0xbfb8aa3b, v60
	v_exp_f32_e32 v180, v180
	v_mul_f32_e32 v227, 0xbfb8aa3b, v55
	v_exp_f32_e32 v227, v227
	s_waitcnt lgkmcnt(0)
	global_store_dwordx2 v[208:209], v[206:207], off offset:288
	v_mul_f32_e32 v206, 0xbfb8aa3b, v61
	v_mul_f32_e32 v207, 0xbfb8aa3b, v62
	v_mul_f32_e32 v208, 0xbfb8aa3b, v63
	v_exp_f32_e32 v206, v206
	v_exp_f32_e32 v207, v207
	v_exp_f32_e32 v208, v208
	v_add_f32_e32 v180, 1.0, v180
	v_add_f32_e32 v206, 1.0, v206
	v_add_f32_e32 v207, 1.0, v207
	v_add_f32_e32 v208, 1.0, v208
	v_rcp_f32_e32 v180, v180
	v_rcp_f32_e32 v206, v206
	v_rcp_f32_e32 v207, v207
	v_rcp_f32_e32 v208, v208
	v_add_f32_e32 v227, 1.0, v227
	v_cvt_pk_bf16_f32 v180, v180, v206
	ds_bpermute_b32 v206, v226, v180
	v_cvt_pk_bf16_f32 v207, v207, v208
	ds_bpermute_b32 v207, v226, v207
	v_lshl_add_u64 v[208:209], v[130:131], 0, s[4:5]
	s_mov_b32 s4, 0x80000
	v_add_co_u32_e32 v228, vcc, s4, v130
	v_mul_f32_e32 v180, 0xbfb8aa3b, v52
	s_nop 0
	v_addc_co_u32_e32 v229, vcc, 0, v131, vcc
	s_waitcnt lgkmcnt(0)
	global_store_dwordx2 v[228:229], v[206:207], off
	v_mul_f32_e32 v206, 0xbfb8aa3b, v53
	v_mul_f32_e32 v207, 0xbfb8aa3b, v54
	v_exp_f32_e32 v180, v180
	v_exp_f32_e32 v206, v206
	v_exp_f32_e32 v207, v207
	v_rcp_f32_e32 v227, v227
	v_add_f32_e32 v180, 1.0, v180
	v_add_f32_e32 v206, 1.0, v206
	v_add_f32_e32 v207, 1.0, v207
	v_rcp_f32_e32 v180, v180
	v_rcp_f32_e32 v206, v206
	v_rcp_f32_e32 v207, v207
	s_mov_b64 s[4:5], 0x90000
	v_cvt_pk_bf16_f32 v180, v180, v206
	v_cvt_pk_bf16_f32 v207, v207, v227
	ds_bpermute_b32 v206, v226, v180
	ds_bpermute_b32 v207, v226, v207
	v_exp_f32_e32 v180, v146
	v_exp_f32_e32 v227, v141
	s_waitcnt lgkmcnt(0)
	global_store_dwordx2 v[208:209], v[206:207], off offset:32
	v_exp_f32_e32 v206, v145
	v_exp_f32_e32 v207, v144
	v_add_f32_e32 v180, 1.0, v180
	v_add_f32_e32 v227, 1.0, v227
	v_add_f32_e32 v206, 1.0, v206
	v_add_f32_e32 v207, 1.0, v207
	v_rcp_f32_e32 v180, v180
	v_rcp_f32_e32 v206, v206
	v_rcp_f32_e32 v207, v207
	v_rcp_f32_e32 v227, v227
	v_cvt_pk_bf16_f32 v180, v180, v206
	ds_bpermute_b32 v206, v226, v180
	v_cvt_pk_bf16_f32 v207, v207, v227
	ds_bpermute_b32 v207, v226, v207
	v_exp_f32_e32 v180, v140
	v_exp_f32_e32 v227, v137
	s_waitcnt lgkmcnt(0)
	global_store_dwordx2 v[208:209], v[206:207], off offset:256
	v_exp_f32_e32 v206, v139
	v_exp_f32_e32 v207, v138
	v_add_f32_e32 v180, 1.0, v180
	v_add_f32_e32 v227, 1.0, v227
	v_add_f32_e32 v206, 1.0, v206
	v_add_f32_e32 v207, 1.0, v207
	v_rcp_f32_e32 v180, v180
	v_rcp_f32_e32 v206, v206
	v_rcp_f32_e32 v207, v207
	v_rcp_f32_e32 v227, v227
	v_cvt_pk_bf16_f32 v180, v180, v206
	ds_bpermute_b32 v206, v226, v180
	v_cvt_pk_bf16_f32 v207, v207, v227
	ds_bpermute_b32 v207, v226, v207
	v_mul_f32_e32 v180, 0xbfb8aa3b, v44
	v_exp_f32_e32 v180, v180
	v_mul_f32_e32 v227, 0xbfb8aa3b, v39
	v_exp_f32_e32 v227, v227
	s_waitcnt lgkmcnt(0)
	global_store_dwordx2 v[208:209], v[206:207], off offset:288
	v_mul_f32_e32 v206, 0xbfb8aa3b, v45
	v_mul_f32_e32 v207, 0xbfb8aa3b, v46
	v_mul_f32_e32 v208, 0xbfb8aa3b, v47
	v_exp_f32_e32 v206, v206
	v_exp_f32_e32 v207, v207
	v_exp_f32_e32 v208, v208
	v_add_f32_e32 v180, 1.0, v180
	v_add_f32_e32 v206, 1.0, v206
	v_add_f32_e32 v207, 1.0, v207
	v_add_f32_e32 v208, 1.0, v208
	v_rcp_f32_e32 v180, v180
	v_rcp_f32_e32 v206, v206
	v_rcp_f32_e32 v207, v207
	v_rcp_f32_e32 v208, v208
	v_add_f32_e32 v227, 1.0, v227
	v_cvt_pk_bf16_f32 v180, v180, v206
	ds_bpermute_b32 v206, v226, v180
	v_cvt_pk_bf16_f32 v207, v207, v208
	ds_bpermute_b32 v207, v226, v207
	v_lshl_add_u64 v[208:209], v[130:131], 0, s[4:5]
	s_mov_b32 s4, 0x90000
	v_add_co_u32_e32 v228, vcc, s4, v130
	v_mul_f32_e32 v180, 0xbfb8aa3b, v36
	s_nop 0
	v_addc_co_u32_e32 v229, vcc, 0, v131, vcc
	s_waitcnt lgkmcnt(0)
	global_store_dwordx2 v[228:229], v[206:207], off
	v_mul_f32_e32 v206, 0xbfb8aa3b, v37
	v_mul_f32_e32 v207, 0xbfb8aa3b, v38
	v_exp_f32_e32 v180, v180
	v_exp_f32_e32 v206, v206
	v_exp_f32_e32 v207, v207
	v_rcp_f32_e32 v227, v227
	v_add_f32_e32 v180, 1.0, v180
	v_add_f32_e32 v206, 1.0, v206
	v_add_f32_e32 v207, 1.0, v207
	v_rcp_f32_e32 v180, v180
	v_rcp_f32_e32 v206, v206
	v_rcp_f32_e32 v207, v207
	s_mov_b64 s[4:5], 0xa0000
	v_cvt_pk_bf16_f32 v180, v180, v206
	v_cvt_pk_bf16_f32 v207, v207, v227
	ds_bpermute_b32 v206, v226, v180
	ds_bpermute_b32 v207, v226, v207
	v_exp_f32_e32 v180, v136
	v_exp_f32_e32 v227, v132
	s_waitcnt lgkmcnt(0)
	global_store_dwordx2 v[208:209], v[206:207], off offset:32
	v_exp_f32_e32 v206, v135
	v_exp_f32_e32 v207, v134
	v_add_f32_e32 v180, 1.0, v180
	v_add_f32_e32 v227, 1.0, v227
	v_add_f32_e32 v206, 1.0, v206
	v_add_f32_e32 v207, 1.0, v207
	v_rcp_f32_e32 v180, v180
	v_rcp_f32_e32 v206, v206
	v_rcp_f32_e32 v207, v207
	v_rcp_f32_e32 v227, v227
	v_cvt_pk_bf16_f32 v180, v180, v206
	ds_bpermute_b32 v206, v226, v180
	v_cvt_pk_bf16_f32 v207, v207, v227
	ds_bpermute_b32 v207, v226, v207
	v_mul_f32_e32 v180, 0xbfb8aa3b, v32
	v_mul_f32_e32 v227, 0xbfb8aa3b, v35
	v_exp_f32_e32 v180, v180
	v_exp_f32_e32 v227, v227
	s_waitcnt lgkmcnt(0)
	global_store_dwordx2 v[208:209], v[206:207], off offset:256
	v_mul_f32_e32 v206, 0xbfb8aa3b, v33
	v_mul_f32_e32 v207, 0xbfb8aa3b, v34
	v_exp_f32_e32 v206, v206
	v_exp_f32_e32 v207, v207
	v_add_f32_e32 v180, 1.0, v180
	v_add_f32_e32 v227, 1.0, v227
	v_add_f32_e32 v206, 1.0, v206
	v_add_f32_e32 v207, 1.0, v207
	v_rcp_f32_e32 v180, v180
	v_rcp_f32_e32 v206, v206
	v_rcp_f32_e32 v207, v207
	v_rcp_f32_e32 v227, v227
	v_cvt_pk_bf16_f32 v180, v180, v206
	ds_bpermute_b32 v206, v226, v180
	v_cvt_pk_bf16_f32 v207, v207, v227
	ds_bpermute_b32 v207, v226, v207
	v_mul_f32_e32 v180, 0xbfb8aa3b, v28
	v_exp_f32_e32 v180, v180
	v_mul_f32_e32 v227, 0xbfb8aa3b, v23
	v_exp_f32_e32 v227, v227
	s_waitcnt lgkmcnt(0)
	global_store_dwordx2 v[208:209], v[206:207], off offset:288
	v_mul_f32_e32 v206, 0xbfb8aa3b, v29
	v_mul_f32_e32 v207, 0xbfb8aa3b, v30
	v_mul_f32_e32 v208, 0xbfb8aa3b, v31
	v_exp_f32_e32 v206, v206
	v_exp_f32_e32 v207, v207
	v_exp_f32_e32 v208, v208
	v_add_f32_e32 v180, 1.0, v180
	v_add_f32_e32 v206, 1.0, v206
	v_add_f32_e32 v207, 1.0, v207
	v_add_f32_e32 v208, 1.0, v208
	v_rcp_f32_e32 v180, v180
	v_rcp_f32_e32 v206, v206
	v_rcp_f32_e32 v207, v207
	v_rcp_f32_e32 v208, v208
	v_add_f32_e32 v227, 1.0, v227
	v_cvt_pk_bf16_f32 v180, v180, v206
	ds_bpermute_b32 v206, v226, v180
	v_cvt_pk_bf16_f32 v207, v207, v208
	ds_bpermute_b32 v207, v226, v207
	v_lshl_add_u64 v[208:209], v[130:131], 0, s[4:5]
	s_mov_b32 s4, 0xa0000
	v_add_co_u32_e32 v228, vcc, s4, v130
	v_mul_f32_e32 v180, 0xbfb8aa3b, v20
	s_nop 0
	v_addc_co_u32_e32 v229, vcc, 0, v131, vcc
	s_waitcnt lgkmcnt(0)
	global_store_dwordx2 v[228:229], v[206:207], off
	v_mul_f32_e32 v206, 0xbfb8aa3b, v21
	v_mul_f32_e32 v207, 0xbfb8aa3b, v22
	v_exp_f32_e32 v180, v180
	v_exp_f32_e32 v206, v206
	v_exp_f32_e32 v207, v207
	v_rcp_f32_e32 v227, v227
	v_add_f32_e32 v180, 1.0, v180
	v_add_f32_e32 v206, 1.0, v206
	v_add_f32_e32 v207, 1.0, v207
	v_rcp_f32_e32 v180, v180
	v_rcp_f32_e32 v206, v206
	v_rcp_f32_e32 v207, v207
	s_mov_b64 s[4:5], 0xb0000
	v_cvt_pk_bf16_f32 v180, v180, v206
	v_cvt_pk_bf16_f32 v207, v207, v227
	ds_bpermute_b32 v206, v226, v180
	ds_bpermute_b32 v207, v226, v207
	v_mul_f32_e32 v180, 0xbfb8aa3b, v24
	v_mul_f32_e32 v227, 0xbfb8aa3b, v27
	v_exp_f32_e32 v180, v180
	v_exp_f32_e32 v227, v227
	s_waitcnt lgkmcnt(0)
	global_store_dwordx2 v[208:209], v[206:207], off offset:32
	v_mul_f32_e32 v206, 0xbfb8aa3b, v25
	v_mul_f32_e32 v207, 0xbfb8aa3b, v26
	v_exp_f32_e32 v206, v206
	v_exp_f32_e32 v207, v207
	v_add_f32_e32 v180, 1.0, v180
	v_add_f32_e32 v227, 1.0, v227
	v_add_f32_e32 v206, 1.0, v206
	v_add_f32_e32 v207, 1.0, v207
	v_rcp_f32_e32 v180, v180
	v_rcp_f32_e32 v206, v206
	v_rcp_f32_e32 v207, v207
	v_rcp_f32_e32 v227, v227
	v_cvt_pk_bf16_f32 v180, v180, v206
	ds_bpermute_b32 v206, v226, v180
	v_cvt_pk_bf16_f32 v207, v207, v227
	ds_bpermute_b32 v207, v226, v207
	v_mul_f32_e32 v180, 0xbfb8aa3b, v16
	v_mul_f32_e32 v227, 0xbfb8aa3b, v19
	v_exp_f32_e32 v180, v180
	v_exp_f32_e32 v227, v227
	s_waitcnt lgkmcnt(0)
	global_store_dwordx2 v[208:209], v[206:207], off offset:256
	v_mul_f32_e32 v206, 0xbfb8aa3b, v17
	v_mul_f32_e32 v207, 0xbfb8aa3b, v18
	v_exp_f32_e32 v206, v206
	v_exp_f32_e32 v207, v207
	v_add_f32_e32 v180, 1.0, v180
	v_add_f32_e32 v227, 1.0, v227
	v_add_f32_e32 v206, 1.0, v206
	v_add_f32_e32 v207, 1.0, v207
	v_rcp_f32_e32 v180, v180
	v_rcp_f32_e32 v206, v206
	v_rcp_f32_e32 v207, v207
	v_rcp_f32_e32 v227, v227
	v_cvt_pk_bf16_f32 v180, v180, v206
	ds_bpermute_b32 v206, v226, v180
	v_cvt_pk_bf16_f32 v207, v207, v227
	ds_bpermute_b32 v207, v226, v207
	v_mul_f32_e32 v180, 0xbfb8aa3b, v12
	v_exp_f32_e32 v180, v180
	s_waitcnt lgkmcnt(0)
	global_store_dwordx2 v[208:209], v[206:207], off offset:288
	v_mul_f32_e32 v206, 0xbfb8aa3b, v13
	v_mul_f32_e32 v207, 0xbfb8aa3b, v14
	v_mul_f32_e32 v208, 0xbfb8aa3b, v15
	v_exp_f32_e32 v206, v206
	v_exp_f32_e32 v207, v207
	v_exp_f32_e32 v208, v208
	v_add_f32_e32 v180, 1.0, v180
	v_add_f32_e32 v206, 1.0, v206
	v_add_f32_e32 v207, 1.0, v207
	v_add_f32_e32 v208, 1.0, v208
	v_rcp_f32_e32 v180, v180
	v_rcp_f32_e32 v206, v206
	v_rcp_f32_e32 v207, v207
	v_rcp_f32_e32 v208, v208
	v_cvt_pk_bf16_f32 v180, v180, v206
	ds_bpermute_b32 v206, v226, v180
	v_cvt_pk_bf16_f32 v207, v207, v208
	ds_bpermute_b32 v207, v226, v207
	v_lshl_add_u64 v[208:209], v[130:131], 0, s[4:5]
	s_mov_b32 s4, 0xb0000
	v_add_co_u32_e32 v130, vcc, s4, v130
	v_mul_f32_e32 v180, 0xbfb8aa3b, v6
	s_nop 0
	v_addc_co_u32_e32 v131, vcc, 0, v131, vcc
	s_waitcnt lgkmcnt(0)
	global_store_dwordx2 v[130:131], v[206:207], off
	v_mul_f32_e32 v130, 0xbfb8aa3b, v4
	v_mul_f32_e32 v131, 0xbfb8aa3b, v5
	v_mul_f32_e32 v206, 0xbfb8aa3b, v7
	v_exp_f32_e32 v130, v130
	v_exp_f32_e32 v131, v131
	v_exp_f32_e32 v180, v180
	v_exp_f32_e32 v206, v206
	v_add_f32_e32 v130, 1.0, v130
	v_add_f32_e32 v131, 1.0, v131
	v_add_f32_e32 v180, 1.0, v180
	v_add_f32_e32 v206, 1.0, v206
	v_rcp_f32_e32 v130, v130
	v_rcp_f32_e32 v131, v131
	v_rcp_f32_e32 v180, v180
	v_rcp_f32_e32 v206, v206
	s_mov_b64 s[4:5], 0
	v_cvt_pk_bf16_f32 v130, v130, v131
	ds_bpermute_b32 v130, v226, v130
	v_cvt_pk_bf16_f32 v131, v180, v206
	ds_bpermute_b32 v131, v226, v131
	v_mul_f32_e32 v180, 0xbfb8aa3b, v10
	v_mul_f32_e32 v206, 0xbfb8aa3b, v11
	v_exp_f32_e32 v180, v180
	v_exp_f32_e32 v206, v206
	s_waitcnt lgkmcnt(0)
	global_store_dwordx2 v[208:209], v[130:131], off offset:32
	v_mul_f32_e32 v130, 0xbfb8aa3b, v8
	v_mul_f32_e32 v131, 0xbfb8aa3b, v9
	v_exp_f32_e32 v130, v130
	v_exp_f32_e32 v131, v131
	v_add_f32_e32 v180, 1.0, v180
	v_add_f32_e32 v206, 1.0, v206
	v_add_f32_e32 v130, 1.0, v130
	v_add_f32_e32 v131, 1.0, v131
	v_rcp_f32_e32 v130, v130
	v_rcp_f32_e32 v131, v131
	v_rcp_f32_e32 v180, v180
	v_rcp_f32_e32 v206, v206
	v_cvt_pk_bf16_f32 v130, v130, v131
	ds_bpermute_b32 v130, v226, v130
	v_cvt_pk_bf16_f32 v131, v180, v206
	ds_bpermute_b32 v131, v226, v131
	v_mul_f32_e32 v180, 0xbfb8aa3b, v2
	v_mul_f32_e32 v206, 0xbfb8aa3b, v3
	v_exp_f32_e32 v180, v180
	v_exp_f32_e32 v206, v206
	s_waitcnt lgkmcnt(0)
	global_store_dwordx2 v[208:209], v[130:131], off offset:256
	v_mul_f32_e32 v130, 0xbfb8aa3b, v0
	v_mul_f32_e32 v131, 0xbfb8aa3b, v1
	v_exp_f32_e32 v130, v130
	v_exp_f32_e32 v131, v131
	v_add_f32_e32 v180, 1.0, v180
	v_add_f32_e32 v206, 1.0, v206
	v_add_f32_e32 v130, 1.0, v130
	v_add_f32_e32 v131, 1.0, v131
	v_rcp_f32_e32 v130, v130
	v_rcp_f32_e32 v131, v131
	v_rcp_f32_e32 v180, v180
	v_rcp_f32_e32 v206, v206
	v_cvt_pk_bf16_f32 v130, v130, v131
	ds_bpermute_b32 v130, v226, v130
	v_cvt_pk_bf16_f32 v131, v180, v206
	ds_bpermute_b32 v131, v226, v131
	s_waitcnt lgkmcnt(0)
	global_store_dwordx2 v[208:209], v[130:131], off offset:288

.LBB0_1024:
	s_waitcnt lgkmcnt(0)
	ds_read_b128 v[128:131], v179
	ds_read_b128 v[132:135], v179 offset:1024
	ds_read_b128 v[136:139], v179 offset:2048
	ds_read_b128 v[140:143], v179 offset:3072
	s_add_i32 s62, s36, 2
	s_add_u32 s37, s4, 0xfff80080
	s_addc_u32 s38, s5, -1
	s_cmp_eq_u32 s59, s36
	s_cselect_b32 s36, s58, s60
	s_cselect_b32 s39, s21, s38
	s_cselect_b32 s38, s25, s37
	s_cselect_b32 s37, s23, s61

	s_add_i32 m0, s31, 0xc000
	ds_read_b128 v[144:147], v190
	ds_read_b128 v[148:151], v190 offset:1024
	ds_read_b128 v[152:155], v190 offset:2048
	ds_read_b128 v[156:159], v190 offset:3072
	ds_read_b128 v[180:183], v190 offset:4096
	ds_read_b128 v[184:187], v190 offset:5120
	ds_read_b128 v[194:197], v190 offset:6144
	ds_read_b128 v[198:201], v190 offset:7168
	global_load_lds_dwordx4 v162, s[4:5]
	s_add_i32 m0, s31, 0xe000
	s_nop 0

	global_load_lds_dwordx4 v164, s[4:5]
	s_waitcnt lgkmcnt(8)
	s_barrier
	s_waitcnt lgkmcnt(0)


	v_mfma_f32_16x16x32_bf16 v[124:127], v[128:131], v[144:147], v[124:127]
	v_mfma_f32_16x16x32_bf16 v[120:123], v[136:139], v[144:147], v[120:123]
	v_mfma_f32_16x16x32_bf16 v[116:119], v[128:131], v[152:155], v[116:119]
	v_mfma_f32_16x16x32_bf16 v[104:107], v[136:139], v[152:155], v[104:107]
	v_mfma_f32_16x16x32_bf16 v[96:99], v[128:131], v[180:183], v[96:99]
	v_mfma_f32_16x16x32_bf16 v[88:91], v[136:139], v[180:183], v[88:91]
	v_mfma_f32_16x16x32_bf16 v[80:83], v[128:131], v[194:197], v[80:83]
	v_mfma_f32_16x16x32_bf16 v[72:75], v[136:139], v[194:197], v[72:75]
	v_mfma_f32_16x16x32_bf16 v[124:127], v[132:135], v[148:151], v[124:127]
	v_mfma_f32_16x16x32_bf16 v[120:123], v[140:143], v[148:151], v[120:123]
	v_mfma_f32_16x16x32_bf16 v[116:119], v[132:135], v[156:159], v[116:119]
	v_mfma_f32_16x16x32_bf16 v[104:107], v[140:143], v[156:159], v[104:107]
	v_mfma_f32_16x16x32_bf16 v[96:99], v[132:135], v[184:187], v[96:99]
	v_mfma_f32_16x16x32_bf16 v[88:91], v[140:143], v[184:187], v[88:91]
	v_mfma_f32_16x16x32_bf16 v[80:83], v[132:135], v[198:201], v[80:83]
	v_mfma_f32_16x16x32_bf16 v[72:75], v[140:143], v[198:201], v[72:75]

	s_barrier
	s_add_i32 s63, s52, s42
	s_add_u32 s66, s36, s14
	s_addc_u32 s67, s37, s15
	s_mov_b32 m0, s63
	ds_read_b128 v[202:205], v191
	ds_read_b128 v[206:209], v191 offset:1024
	ds_read_b128 v[222:225], v191 offset:2048
	ds_read_b128 v[226:229], v191 offset:3072
	global_load_lds_dwordx4 v172, s[36:37]
	s_add_i32 m0, s63, 0x2000
	s_nop 0

	global_load_lds_dwordx4 v174, s[36:37]
	s_barrier
	s_waitcnt lgkmcnt(0)


	v_mfma_f32_16x16x32_bf16 v[112:115], v[202:205], v[144:147], v[112:115]
	v_mfma_f32_16x16x32_bf16 v[108:111], v[222:225], v[144:147], v[108:111]
	v_mfma_f32_16x16x32_bf16 v[100:103], v[202:205], v[152:155], v[100:103]
	v_mfma_f32_16x16x32_bf16 v[92:95], v[222:225], v[152:155], v[92:95]
	v_mfma_f32_16x16x32_bf16 v[84:87], v[202:205], v[180:183], v[84:87]
	v_mfma_f32_16x16x32_bf16 v[76:79], v[222:225], v[180:183], v[76:79]
	v_mfma_f32_16x16x32_bf16 v[68:71], v[202:205], v[194:197], v[68:71]
	v_mfma_f32_16x16x32_bf16 v[64:67], v[222:225], v[194:197], v[64:67]
	v_mfma_f32_16x16x32_bf16 v[112:115], v[206:209], v[148:151], v[112:115]
	v_mfma_f32_16x16x32_bf16 v[108:111], v[226:229], v[148:151], v[108:111]
	v_mfma_f32_16x16x32_bf16 v[100:103], v[206:209], v[156:159], v[100:103]
	v_mfma_f32_16x16x32_bf16 v[92:95], v[226:229], v[156:159], v[92:95]
	v_mfma_f32_16x16x32_bf16 v[84:87], v[206:209], v[184:187], v[84:87]
	v_mfma_f32_16x16x32_bf16 v[76:79], v[226:229], v[184:187], v[76:79]
	v_mfma_f32_16x16x32_bf16 v[68:71], v[206:209], v[198:201], v[68:71]
	v_mfma_f32_16x16x32_bf16 v[64:67], v[226:229], v[198:201], v[64:67]

	s_mov_b32 m0, s31
	s_add_u32 s68, s38, s14
	s_addc_u32 s69, s39, s15
	s_barrier
	ds_read_b128 v[144:147], v190 offset:16384
	ds_read_b128 v[148:151], v190 offset:17408
	ds_read_b128 v[152:155], v190 offset:18432
	ds_read_b128 v[156:159], v190 offset:19456
	ds_read_b128 v[180:183], v190 offset:20480
	ds_read_b128 v[184:187], v190 offset:21504
	ds_read_b128 v[194:197], v190 offset:22528
	ds_read_b128 v[198:201], v190 offset:23552
	global_load_lds_dwordx4 v172, s[38:39]
	s_mov_b32 m0, s35
	s_nop 0

	global_load_lds_dwordx4 v174, s[38:39]
	s_barrier
	s_waitcnt lgkmcnt(0)


	v_mfma_f32_16x16x32_bf16 v[60:63], v[128:131], v[144:147], v[60:63]
	v_mfma_f32_16x16x32_bf16 v[56:59], v[136:139], v[144:147], v[56:59]
	v_mfma_f32_16x16x32_bf16 v[52:55], v[128:131], v[152:155], v[52:55]
	v_mfma_f32_16x16x32_bf16 v[40:43], v[136:139], v[152:155], v[40:43]
	v_mfma_f32_16x16x32_bf16 v[36:39], v[128:131], v[180:183], v[36:39]
	v_mfma_f32_16x16x32_bf16 v[24:27], v[136:139], v[180:183], v[24:27]
	v_mfma_f32_16x16x32_bf16 v[20:23], v[128:131], v[194:197], v[20:23]
	v_mfma_f32_16x16x32_bf16 v[8:11], v[136:139], v[194:197], v[8:11]
	v_mfma_f32_16x16x32_bf16 v[60:63], v[132:135], v[148:151], v[60:63]
	v_mfma_f32_16x16x32_bf16 v[56:59], v[140:143], v[148:151], v[56:59]
	v_mfma_f32_16x16x32_bf16 v[52:55], v[132:135], v[156:159], v[52:55]
	v_mfma_f32_16x16x32_bf16 v[40:43], v[140:143], v[156:159], v[40:43]
	v_mfma_f32_16x16x32_bf16 v[36:39], v[132:135], v[184:187], v[36:39]
	v_mfma_f32_16x16x32_bf16 v[24:27], v[140:143], v[184:187], v[24:27]
	v_mfma_f32_16x16x32_bf16 v[20:23], v[132:135], v[198:201], v[20:23]
	v_mfma_f32_16x16x32_bf16 v[8:11], v[140:143], v[198:201], v[8:11]

	s_barrier
	s_add_u32 s64, s36, 0x80000
	s_addc_u32 s65, s37, 0
	s_add_i32 s63, s53, s42
	s_mov_b32 m0, s63
	s_nop 0

	global_load_lds_dwordx4 v172, s[64:65]
	s_add_i32 m0, s63, 0x2000
	s_nop 0

	global_load_lds_dwordx4 v174, s[64:65]
	s_waitcnt vmcnt(6)
	s_barrier

	v_mfma_f32_16x16x32_bf16 v[48:51], v[202:205], v[144:147], v[48:51]
	v_mfma_f32_16x16x32_bf16 v[44:47], v[222:225], v[144:147], v[44:47]
	v_mfma_f32_16x16x32_bf16 v[32:35], v[202:205], v[152:155], v[32:35]
	v_mfma_f32_16x16x32_bf16 v[28:31], v[222:225], v[152:155], v[28:31]
	v_mfma_f32_16x16x32_bf16 v[16:19], v[202:205], v[180:183], v[16:19]
	v_mfma_f32_16x16x32_bf16 v[12:15], v[222:225], v[180:183], v[12:15]
	v_mfma_f32_16x16x32_bf16 v[4:7], v[202:205], v[194:197], v[4:7]
	v_mfma_f32_16x16x32_bf16 v[0:3], v[222:225], v[194:197], v[0:3]
	v_mfma_f32_16x16x32_bf16 v[48:51], v[206:209], v[148:151], v[48:51]
	v_mfma_f32_16x16x32_bf16 v[44:47], v[226:229], v[148:151], v[44:47]
	v_mfma_f32_16x16x32_bf16 v[32:35], v[206:209], v[156:159], v[32:35]
	v_mfma_f32_16x16x32_bf16 v[28:31], v[226:229], v[156:159], v[28:31]
	v_mfma_f32_16x16x32_bf16 v[16:19], v[206:209], v[184:187], v[16:19]
	v_mfma_f32_16x16x32_bf16 v[12:15], v[226:229], v[184:187], v[12:15]
	v_mfma_f32_16x16x32_bf16 v[4:7], v[206:209], v[198:201], v[4:7]
	v_mfma_f32_16x16x32_bf16 v[0:3], v[226:229], v[198:201], v[0:3]

	s_add_i32 s63, 0, 0x18000

	s_barrier
	ds_read_b128 v[128:131], v179 offset:32768
	ds_read_b128 v[132:135], v179 offset:33792
	ds_read_b128 v[136:139], v179 offset:34816
	ds_read_b128 v[140:143], v179 offset:35840
	s_add_u32 s38, s38, 0x80000
	s_addc_u32 s39, s39, 0
	s_mov_b32 m0, s43

	ds_read_b128 v[144:147], v190 offset:32768
	ds_read_b128 v[148:151], v190 offset:33792
	ds_read_b128 v[152:155], v190 offset:34816
	ds_read_b128 v[156:159], v190 offset:35840
	ds_read_b128 v[180:183], v190 offset:36864
	ds_read_b128 v[184:187], v190 offset:37888
	ds_read_b128 v[194:197], v190 offset:38912
	ds_read_b128 v[198:201], v190 offset:39936
	global_load_lds_dwordx4 v172, s[38:39]
	s_mov_b32 m0, s44
	s_nop 0

	global_load_lds_dwordx4 v174, s[38:39]
	s_waitcnt lgkmcnt(8)
	s_barrier
	s_waitcnt lgkmcnt(0)


	v_mfma_f32_16x16x32_bf16 v[124:127], v[128:131], v[144:147], v[124:127]
	v_mfma_f32_16x16x32_bf16 v[120:123], v[136:139], v[144:147], v[120:123]
	v_mfma_f32_16x16x32_bf16 v[116:119], v[128:131], v[152:155], v[116:119]
	v_mfma_f32_16x16x32_bf16 v[104:107], v[136:139], v[152:155], v[104:107]
	v_mfma_f32_16x16x32_bf16 v[96:99], v[128:131], v[180:183], v[96:99]
	v_mfma_f32_16x16x32_bf16 v[88:91], v[136:139], v[180:183], v[88:91]
	v_mfma_f32_16x16x32_bf16 v[80:83], v[128:131], v[194:197], v[80:83]
	v_mfma_f32_16x16x32_bf16 v[72:75], v[136:139], v[194:197], v[72:75]
	v_mfma_f32_16x16x32_bf16 v[124:127], v[132:135], v[148:151], v[124:127]
	v_mfma_f32_16x16x32_bf16 v[120:123], v[140:143], v[148:151], v[120:123]
	v_mfma_f32_16x16x32_bf16 v[116:119], v[132:135], v[156:159], v[116:119]
	v_mfma_f32_16x16x32_bf16 v[104:107], v[140:143], v[156:159], v[104:107]
	v_mfma_f32_16x16x32_bf16 v[96:99], v[132:135], v[184:187], v[96:99]
	v_mfma_f32_16x16x32_bf16 v[88:91], v[140:143], v[184:187], v[88:91]
	v_mfma_f32_16x16x32_bf16 v[80:83], v[132:135], v[198:201], v[80:83]
	v_mfma_f32_16x16x32_bf16 v[72:75], v[140:143], v[198:201], v[72:75]

	s_barrier
	s_add_i32 s38, 0, 0x1c000
	s_add_i32 s39, s63, s42


	s_mov_b32 m0, s39
	ds_read_b128 v[202:205], v191 offset:32768
	ds_read_b128 v[206:209], v191 offset:33792
	ds_read_b128 v[222:225], v191 offset:34816
	ds_read_b128 v[226:229], v191 offset:35840
	global_load_lds_dwordx4 v172, s[66:67]
	s_add_i32 m0, s39, 0x2000
	s_nop 0

	global_load_lds_dwordx4 v174, s[66:67]
	s_barrier
	s_waitcnt lgkmcnt(0)


	v_mfma_f32_16x16x32_bf16 v[112:115], v[202:205], v[144:147], v[112:115]
	v_mfma_f32_16x16x32_bf16 v[108:111], v[222:225], v[144:147], v[108:111]
	v_mfma_f32_16x16x32_bf16 v[100:103], v[202:205], v[152:155], v[100:103]
	v_mfma_f32_16x16x32_bf16 v[92:95], v[222:225], v[152:155], v[92:95]
	v_mfma_f32_16x16x32_bf16 v[84:87], v[202:205], v[180:183], v[84:87]
	v_mfma_f32_16x16x32_bf16 v[76:79], v[222:225], v[180:183], v[76:79]
	v_mfma_f32_16x16x32_bf16 v[68:71], v[202:205], v[194:197], v[68:71]
	v_mfma_f32_16x16x32_bf16 v[64:67], v[222:225], v[194:197], v[64:67]
	v_mfma_f32_16x16x32_bf16 v[112:115], v[206:209], v[148:151], v[112:115]
	v_mfma_f32_16x16x32_bf16 v[108:111], v[226:229], v[148:151], v[108:111]
	v_mfma_f32_16x16x32_bf16 v[100:103], v[206:209], v[156:159], v[100:103]
	v_mfma_f32_16x16x32_bf16 v[92:95], v[226:229], v[156:159], v[92:95]
	v_mfma_f32_16x16x32_bf16 v[84:87], v[206:209], v[184:187], v[84:87]
	v_mfma_f32_16x16x32_bf16 v[76:79], v[226:229], v[184:187], v[76:79]
	v_mfma_f32_16x16x32_bf16 v[68:71], v[206:209], v[198:201], v[68:71]
	v_mfma_f32_16x16x32_bf16 v[64:67], v[226:229], v[198:201], v[64:67]

	s_mov_b32 m0, s48

	s_barrier
	ds_read_b128 v[144:147], v190 offset:49152
	ds_read_b128 v[148:151], v190 offset:50176
	ds_read_b128 v[152:155], v190 offset:51200
	ds_read_b128 v[156:159], v190 offset:52224
	ds_read_b128 v[180:183], v190 offset:53248
	ds_read_b128 v[184:187], v190 offset:54272
	ds_read_b128 v[194:197], v190 offset:55296
	ds_read_b128 v[198:201], v190 offset:56320
	global_load_lds_dwordx4 v172, s[68:69]
	s_mov_b32 m0, s49
	s_nop 0

	global_load_lds_dwordx4 v174, s[68:69]
	s_barrier
	s_waitcnt lgkmcnt(0)


	v_mfma_f32_16x16x32_bf16 v[60:63], v[128:131], v[144:147], v[60:63]
	v_mfma_f32_16x16x32_bf16 v[56:59], v[136:139], v[144:147], v[56:59]
	v_mfma_f32_16x16x32_bf16 v[52:55], v[128:131], v[152:155], v[52:55]
	v_mfma_f32_16x16x32_bf16 v[40:43], v[136:139], v[152:155], v[40:43]
	v_mfma_f32_16x16x32_bf16 v[36:39], v[128:131], v[180:183], v[36:39]
	v_mfma_f32_16x16x32_bf16 v[24:27], v[136:139], v[180:183], v[24:27]
	v_mfma_f32_16x16x32_bf16 v[20:23], v[128:131], v[194:197], v[20:23]
	v_mfma_f32_16x16x32_bf16 v[8:11], v[136:139], v[194:197], v[8:11]
	v_mfma_f32_16x16x32_bf16 v[60:63], v[132:135], v[148:151], v[60:63]
	v_mfma_f32_16x16x32_bf16 v[56:59], v[140:143], v[148:151], v[56:59]
	v_mfma_f32_16x16x32_bf16 v[52:55], v[132:135], v[156:159], v[52:55]
	v_mfma_f32_16x16x32_bf16 v[40:43], v[140:143], v[156:159], v[40:43]
	v_mfma_f32_16x16x32_bf16 v[36:39], v[132:135], v[184:187], v[36:39]
	v_mfma_f32_16x16x32_bf16 v[24:27], v[140:143], v[184:187], v[24:27]
	v_mfma_f32_16x16x32_bf16 v[20:23], v[132:135], v[198:201], v[20:23]
	v_mfma_f32_16x16x32_bf16 v[8:11], v[140:143], v[198:201], v[8:11]

	s_barrier
	s_add_u32 s36, s36, 0x80080
	s_addc_u32 s37, s37, 0
	s_add_i32 s38, s38, s42
	s_mov_b32 m0, s38
	s_add_u32 s4, s4, 0x100
	s_addc_u32 s5, s5, 0

	global_load_lds_dwordx4 v172, s[36:37]
	s_add_i32 m0, s38, 0x2000
	s_add_u32 s60, s60, 0x100
	s_addc_u32 s61, s61, 0

	global_load_lds_dwordx4 v174, s[36:37]
	s_waitcnt vmcnt(6)
	s_barrier

	v_mfma_f32_16x16x32_bf16 v[48:51], v[202:205], v[144:147], v[48:51]
	v_mfma_f32_16x16x32_bf16 v[44:47], v[222:225], v[144:147], v[44:47]
	v_mfma_f32_16x16x32_bf16 v[32:35], v[202:205], v[152:155], v[32:35]
	v_mfma_f32_16x16x32_bf16 v[28:31], v[222:225], v[152:155], v[28:31]
	v_mfma_f32_16x16x32_bf16 v[16:19], v[202:205], v[180:183], v[16:19]
	v_mfma_f32_16x16x32_bf16 v[12:15], v[222:225], v[180:183], v[12:15]
	v_mfma_f32_16x16x32_bf16 v[4:7], v[202:205], v[194:197], v[4:7]
	v_mfma_f32_16x16x32_bf16 v[0:3], v[222:225], v[194:197], v[0:3]
	v_mfma_f32_16x16x32_bf16 v[48:51], v[206:209], v[148:151], v[48:51]
	v_mfma_f32_16x16x32_bf16 v[44:47], v[226:229], v[148:151], v[44:47]
	v_mfma_f32_16x16x32_bf16 v[32:35], v[206:209], v[156:159], v[32:35]
	v_mfma_f32_16x16x32_bf16 v[28:31], v[226:229], v[156:159], v[28:31]
	v_mfma_f32_16x16x32_bf16 v[16:19], v[206:209], v[184:187], v[16:19]
	v_mfma_f32_16x16x32_bf16 v[12:15], v[226:229], v[184:187], v[12:15]
	v_mfma_f32_16x16x32_bf16 v[4:7], v[206:209], v[198:201], v[4:7]
	v_mfma_f32_16x16x32_bf16 v[0:3], v[226:229], v[198:201], v[0:3]


	s_cmp_ge_i32 s62, s17
	s_mov_b32 s36, s62
	s_barrier
	s_cbranch_scc0 .LBB0_1024
	v_mov_b32_e32 v128, v210
	v_mov_b32_e32 v129, v169
	s_cmp_lt_i32 s12, 0
	v_lshl_add_u32 v128, v128, 4, v129
	v_ashrrev_i32_e32 v166, 2, v128
	v_and_b32_e32 v160, 3, v129
	v_and_b32_e32 v128, -4, v128
	v_lshl_add_u32 v193, v160, 6, v128
	s_mov_b64 s[4:5], -1
	s_cbranch_scc0 .LBB0_1043
	s_lshl_b32 s4, s30, 8
	v_lshl_or_b32 v128, v160, 2, s4
	s_lshl_b32 s4, s34, 8
	v_or_b32_e32 v180, s47, v128
	s_add_i32 s4, s4, s46
	v_readlane_b32 s60, v254, 6
	v_ashrrev_i32_e32 v181, 31, v180
	v_add_u32_e32 v184, s4, v166
	s_cmp_lt_i32 s34, 32
	v_readlane_b32 s61, v254, 7
	v_lshlrev_b64 v[128:129], 2, v[180:181]
	v_readlane_b32 s62, v254, 8
	v_readlane_b32 s63, v254, 9
	v_readlane_b32 s64, v254, 10
	v_readlane_b32 s65, v254, 11
	v_readlane_b32 s66, v254, 12
	v_readlane_b32 s67, v254, 13
	v_readlane_b32 s68, v254, 14
	v_readlane_b32 s69, v254, 15
	v_readlane_b32 s70, v254, 16
	v_readlane_b32 s71, v254, 17
	v_readlane_b32 s72, v254, 18
	v_readlane_b32 s73, v254, 19
	v_readlane_b32 s74, v254, 20
	v_readlane_b32 s75, v254, 21
	s_cselect_b32 s5, s61, s51
	s_cselect_b32 s4, s60, s50
	v_ashrrev_i32_e32 v185, 31, v184
	v_lshl_add_u64 v[182:183], s[4:5], 0, v[128:129]
	v_lshlrev_b64 v[130:131], 13, v[184:185]
	v_readlane_b32 s60, v254, 22
	v_lshl_add_u64 v[136:137], v[182:183], 0, v[130:131]
	v_readlane_b32 s61, v254, 23
	v_readlane_b32 s68, v254, 30
	v_readlane_b32 s69, v254, 31
	global_load_dwordx4 v[196:199], v[136:137], off nt
	global_load_dwordx4 v[200:203], v[136:137], off offset:64 nt
	global_load_dwordx4 v[204:207], v[136:137], off offset:512 nt
	s_mov_b64 s[60:61], s[68:69]
	v_lshl_add_u64 v[138:139], s[60:61], 0, v[128:129]
	global_load_dwordx4 v[140:143], v[138:139], off
	global_load_dwordx4 v[132:135], v[138:139], off offset:64
	global_load_dwordx4 v[128:131], v[138:139], off offset:512
	global_load_dwordx4 v[222:225], v[136:137], off offset:576 nt
	v_and_b32_e32 v145, 64, v192
	global_load_dwordx4 v[136:139], v[138:139], off offset:576
	v_xor_b32_e32 v144, 1, v192
	v_add_u32_e32 v194, 64, v145
	v_add_u32_e32 v186, 16, v184
	v_cmp_lt_i32_e64 s[4:5], v144, v194
	v_ashrrev_i32_e32 v187, 31, v186
	ds_bpermute_b32 v188, v193, v124
	v_cndmask_b32_e64 v195, v192, v144, s[4:5]
	v_lshlrev_b64 v[144:145], 13, v[186:187]
	v_lshl_add_u64 v[144:145], v[182:183], 0, v[144:145]
	global_load_dwordx4 v[156:159], v[144:145], off nt
	global_load_dwordx4 v[152:155], v[144:145], off offset:64 nt
	global_load_dwordx4 v[148:151], v[144:145], off offset:512 nt
	s_nop 0
	global_load_dwordx4 v[144:147], v[144:145], off offset:576 nt
	ds_bpermute_b32 v189, v193, v125
	ds_bpermute_b32 v208, v193, v126
	ds_bpermute_b32 v209, v193, v127
	ds_bpermute_b32 v226, v193, v120
	ds_bpermute_b32 v227, v193, v121
	ds_bpermute_b32 v228, v193, v122
	ds_bpermute_b32 v229, v193, v123
	ds_bpermute_b32 v230, v193, v112
	ds_bpermute_b32 v231, v193, v113
	v_readlane_b32 s64, v254, 26
	v_readlane_b32 s65, v254, 27
	v_readlane_b32 s66, v254, 28
	v_readlane_b32 s67, v254, 29
	v_readlane_b32 s72, v254, 34
	v_readlane_b32 s73, v254, 35
	v_readlane_b32 s74, v254, 36
	v_readlane_b32 s75, v254, 37
	s_mov_b64 s[64:65], s[72:73]
	ds_bpermute_b32 v232, v193, v114
	ds_bpermute_b32 v233, v193, v115
	v_lshlrev_b64 v[234:235], 11, v[184:185]
	s_mov_b64 s[66:67], s[74:75]
	v_lshl_add_u64 v[234:235], v[234:235], 0, v[180:181]
	v_xor_b32_e32 v167, 2, v192
	v_lshl_add_u64 v[236:237], v[234:235], 2, s[66:67]
	v_readlane_b32 s2, v254, 54
	v_cmp_lt_i32_e64 s[4:5], v167, v194
	v_lshlrev_b32_e32 v194, 2, v195
	v_lshlrev_b64 v[234:235], 1, v[234:235]
	v_readlane_b32 s3, v254, 55
	v_or_b32_e32 v240, 32, v234
	v_mov_b32_e32 v241, v235
	v_lshl_add_u64 v[238:239], s[2:3], 0, v[234:235]
	v_lshl_add_u64 v[240:241], s[2:3], 0, v[240:241]
	v_cndmask_b32_e64 v167, v192, v167, s[4:5]
	v_lshlrev_b32_e32 v167, 2, v167
	v_cmp_eq_u32_e32 vcc, 0, v160
	v_readlane_b32 s62, v254, 24
	v_readlane_b32 s63, v254, 25
	v_readlane_b32 s70, v254, 32
	v_readlane_b32 s71, v254, 33
	s_waitcnt vmcnt(0) lgkmcnt(0)
	v_pk_add_f32 v[198:199], v[198:199], v[208:209]
	v_pk_add_f32 v[196:197], v[196:197], v[188:189]
	v_pk_add_f32 v[202:203], v[202:203], v[228:229]
	v_pk_add_f32 v[200:201], v[200:201], v[226:227]
	v_pk_add_f32 v[204:205], v[204:205], v[230:231]
	v_mul_f32_e32 v195, v197, v197
	v_mul_f32_e32 v221, v199, v199
	global_store_dwordx4 v[236:237], v[196:199], off
	v_pk_mul_f32 v[188:189], v[142:143], v[198:199]
	v_pk_mul_f32 v[208:209], v[140:141], v[196:197]
	v_mul_f32_e32 v199, v201, v201
	v_mul_f32_e32 v230, v203, v203
	v_pk_mul_f32 v[226:227], v[134:135], v[202:203]
	v_pk_mul_f32 v[228:229], v[132:133], v[200:201]
	v_fmac_f32_e32 v195, v196, v196
	v_fmac_f32_e32 v221, v198, v198
	v_cvt_pk_bf16_f32 v196, v208, v209
	v_cvt_pk_bf16_f32 v197, v188, v189
	v_fmac_f32_e32 v199, v200, v200
	v_fmac_f32_e32 v230, v202, v202
	v_pk_add_f32 v[206:207], v[206:207], v[232:233]
	v_cvt_pk_bf16_f32 v188, v228, v229
	v_cvt_pk_bf16_f32 v189, v226, v227
	v_add_f32_e32 v195, v195, v221
	global_store_dwordx2 v[238:239], v[196:197], off
	v_add_f32_e32 v196, v199, v230
	global_store_dwordx4 v[236:237], v[200:203], off offset:64
	global_store_dwordx2 v[240:241], v[188:189], off
	v_add_f32_e32 v188, v195, v196
	v_mul_f32_e32 v189, v205, v205
	v_mul_f32_e32 v195, v207, v207
	v_fmac_f32_e32 v189, v204, v204
	v_fmac_f32_e32 v195, v206, v206
	ds_bpermute_b32 v200, v193, v108
	ds_bpermute_b32 v198, v193, v110
	ds_bpermute_b32 v199, v193, v111
	ds_bpermute_b32 v201, v193, v109
	v_add_f32_e32 v189, v189, v195
	v_add_f32_e32 v195, v188, v189
	v_pk_mul_f32 v[188:189], v[130:131], v[206:207]
	v_pk_mul_f32 v[196:197], v[128:129], v[204:205]
	global_store_dwordx4 v[236:237], v[204:207], off offset:512
	v_cvt_pk_bf16_f32 v196, v196, v197
	v_cvt_pk_bf16_f32 v197, v188, v189
	v_or_b32_e32 v188, 0x100, v234
	v_mov_b32_e32 v189, v235
	v_lshl_add_u64 v[188:189], s[2:3], 0, v[188:189]
	global_store_dwordx2 v[188:189], v[196:197], off
	s_waitcnt lgkmcnt(1)
	v_pk_add_f32 v[198:199], v[224:225], v[198:199]
	s_waitcnt lgkmcnt(0)
	v_pk_add_f32 v[196:197], v[222:223], v[200:201]
	v_mul_f32_e32 v189, v199, v199
	v_mul_f32_e32 v188, v197, v197
	v_fmac_f32_e32 v188, v196, v196
	v_fmac_f32_e32 v189, v198, v198
	v_add_f32_e32 v188, v188, v189
	v_add_f32_e32 v195, v195, v188
	ds_bpermute_b32 v200, v194, v195
	v_pk_mul_f32 v[188:189], v[136:137], v[196:197]
	global_store_dwordx4 v[236:237], v[196:199], off offset:576
	v_or_b32_e32 v234, 0x120, v234
	s_nop 0
	v_cvt_pk_bf16_f32 v196, v188, v189
	s_waitcnt lgkmcnt(0)
	v_add_f32_e32 v188, v195, v200
	ds_bpermute_b32 v189, v167, v188
	v_pk_mul_f32 v[198:199], v[138:139], v[198:199]
	s_nop 0
	v_cvt_pk_bf16_f32 v197, v198, v199
	v_lshl_add_u64 v[198:199], s[2:3], 0, v[234:235]
	global_store_dwordx2 v[198:199], v[196:197], off
	s_and_saveexec_b64 s[4:5], vcc
	s_cbranch_execz .LBB0_1028
	s_waitcnt lgkmcnt(0)
	v_add_f32_e32 v195, v188, v189
	s_lshl_b32 s36, s30, 2
	v_lshlrev_b64 v[188:189], 7, v[184:185]
	s_ashr_i32 s37, s36, 31
	v_lshl_add_u64 v[188:189], s[10:11], 0, v[188:189]
	v_lshl_add_u64 v[188:189], s[36:37], 2, v[188:189]
	s_lshl_b32 s36, s45, 2
	s_mov_b32 s37, s13
	v_lshl_add_u64 v[188:189], v[188:189], 0, s[36:37]
	global_store_dword v[188:189], v195, off

.LBB0_1167:
	ds_read_b128 v[148:151], v143
	ds_read_b128 v[152:155], v143 offset:1024
	ds_read_b128 v[156:159], v143 offset:2048
	ds_read_b128 v[160:163], v143 offset:3072
	s_add_u32 s24, s22, 0xfff80080
	s_addc_u32 s25, s23, -1
	s_cmp_eq_u32 s53, 28
	s_cselect_b32 s27, s15, s25
	s_cselect_b32 s26, s49, s24
	s_cselect_b32 s25, s13, s52
	s_cselect_b32 s24, s50, s51

	s_add_i32 m0, s21, 0xc000
	ds_read_b128 v[164:167], v145
	ds_read_b128 v[176:179], v145 offset:1024
	ds_read_b128 v[180:183], v145 offset:2048
	ds_read_b128 v[184:187], v145 offset:3072
	ds_read_b128 v[188:191], v145 offset:4096
	ds_read_b128 v[192:195], v145 offset:5120
	ds_read_b128 v[196:199], v145 offset:6144
	ds_read_b128 v[200:203], v145 offset:7168
	global_load_lds_dwordx4 v128, s[22:23]
	s_add_i32 m0, s21, 0xe000
	s_nop 0

	global_load_lds_dwordx4 v130, s[22:23]
	s_waitcnt lgkmcnt(8)
	s_barrier
	s_waitcnt lgkmcnt(0)


	v_mfma_f32_16x16x32_bf16 v[124:127], v[148:151], v[164:167], v[124:127]
	v_mfma_f32_16x16x32_bf16 v[120:123], v[156:159], v[164:167], v[120:123]
	v_mfma_f32_16x16x32_bf16 v[116:119], v[148:151], v[180:183], v[116:119]
	v_mfma_f32_16x16x32_bf16 v[104:107], v[156:159], v[180:183], v[104:107]
	v_mfma_f32_16x16x32_bf16 v[96:99], v[148:151], v[188:191], v[96:99]
	v_mfma_f32_16x16x32_bf16 v[88:91], v[156:159], v[188:191], v[88:91]
	v_mfma_f32_16x16x32_bf16 v[80:83], v[148:151], v[196:199], v[80:83]
	v_mfma_f32_16x16x32_bf16 v[72:75], v[156:159], v[196:199], v[72:75]
	v_mfma_f32_16x16x32_bf16 v[124:127], v[152:155], v[176:179], v[124:127]
	v_mfma_f32_16x16x32_bf16 v[120:123], v[160:163], v[176:179], v[120:123]
	v_mfma_f32_16x16x32_bf16 v[116:119], v[152:155], v[184:187], v[116:119]
	v_mfma_f32_16x16x32_bf16 v[104:107], v[160:163], v[184:187], v[104:107]
	v_mfma_f32_16x16x32_bf16 v[96:99], v[152:155], v[192:195], v[96:99]
	v_mfma_f32_16x16x32_bf16 v[88:91], v[160:163], v[192:195], v[88:91]
	v_mfma_f32_16x16x32_bf16 v[80:83], v[152:155], v[200:203], v[80:83]
	v_mfma_f32_16x16x32_bf16 v[72:75], v[160:163], v[200:203], v[72:75]

	s_barrier
	s_add_i32 s54, s45, s31
	s_add_u32 s66, s24, s10
	s_addc_u32 s67, s25, s11
	s_mov_b32 m0, s54
	ds_read_b128 v[204:207], v147
	ds_read_b128 v[218:221], v147 offset:1024
	ds_read_b128 v[222:225], v147 offset:2048
	ds_read_b128 v[226:229], v147 offset:3072
	global_load_lds_dwordx4 v172, s[24:25]
	s_add_i32 m0, s54, 0x2000
	s_nop 0

	global_load_lds_dwordx4 v174, s[24:25]
	s_barrier
	s_waitcnt lgkmcnt(0)


	v_mfma_f32_16x16x32_bf16 v[112:115], v[204:207], v[164:167], v[112:115]
	v_mfma_f32_16x16x32_bf16 v[108:111], v[222:225], v[164:167], v[108:111]
	v_mfma_f32_16x16x32_bf16 v[100:103], v[204:207], v[180:183], v[100:103]
	v_mfma_f32_16x16x32_bf16 v[92:95], v[222:225], v[180:183], v[92:95]
	v_mfma_f32_16x16x32_bf16 v[84:87], v[204:207], v[188:191], v[84:87]
	v_mfma_f32_16x16x32_bf16 v[76:79], v[222:225], v[188:191], v[76:79]
	v_mfma_f32_16x16x32_bf16 v[68:71], v[204:207], v[196:199], v[68:71]
	v_mfma_f32_16x16x32_bf16 v[64:67], v[222:225], v[196:199], v[64:67]
	v_mfma_f32_16x16x32_bf16 v[112:115], v[218:221], v[176:179], v[112:115]
	v_mfma_f32_16x16x32_bf16 v[108:111], v[226:229], v[176:179], v[108:111]
	v_mfma_f32_16x16x32_bf16 v[100:103], v[218:221], v[184:187], v[100:103]
	v_mfma_f32_16x16x32_bf16 v[92:95], v[226:229], v[184:187], v[92:95]
	v_mfma_f32_16x16x32_bf16 v[84:87], v[218:221], v[192:195], v[84:87]
	v_mfma_f32_16x16x32_bf16 v[76:79], v[226:229], v[192:195], v[76:79]
	v_mfma_f32_16x16x32_bf16 v[68:71], v[218:221], v[200:203], v[68:71]
	v_mfma_f32_16x16x32_bf16 v[64:67], v[226:229], v[200:203], v[64:67]

	s_mov_b32 m0, s21
	s_add_u32 s68, s26, s10
	s_addc_u32 s69, s27, s11
	s_barrier
	ds_read_b128 v[164:167], v145 offset:16384
	ds_read_b128 v[176:179], v145 offset:17408
	ds_read_b128 v[180:183], v145 offset:18432
	ds_read_b128 v[184:187], v145 offset:19456
	ds_read_b128 v[188:191], v145 offset:20480
	ds_read_b128 v[192:195], v145 offset:21504
	ds_read_b128 v[196:199], v145 offset:22528
	ds_read_b128 v[200:203], v145 offset:23552
	global_load_lds_dwordx4 v172, s[26:27]
	s_mov_b32 m0, s35
	s_nop 0

	global_load_lds_dwordx4 v174, s[26:27]
	s_barrier
	s_waitcnt lgkmcnt(0)


	v_mfma_f32_16x16x32_bf16 v[60:63], v[148:151], v[164:167], v[60:63]
	v_mfma_f32_16x16x32_bf16 v[56:59], v[156:159], v[164:167], v[56:59]
	v_mfma_f32_16x16x32_bf16 v[48:51], v[148:151], v[180:183], v[48:51]
	v_mfma_f32_16x16x32_bf16 v[40:43], v[156:159], v[180:183], v[40:43]
	v_mfma_f32_16x16x32_bf16 v[32:35], v[148:151], v[188:191], v[32:35]
	v_mfma_f32_16x16x32_bf16 v[24:27], v[156:159], v[188:191], v[24:27]
	v_mfma_f32_16x16x32_bf16 v[16:19], v[148:151], v[196:199], v[16:19]
	v_mfma_f32_16x16x32_bf16 v[8:11], v[156:159], v[196:199], v[8:11]
	v_mfma_f32_16x16x32_bf16 v[60:63], v[152:155], v[176:179], v[60:63]
	v_mfma_f32_16x16x32_bf16 v[56:59], v[160:163], v[176:179], v[56:59]
	v_mfma_f32_16x16x32_bf16 v[48:51], v[152:155], v[184:187], v[48:51]
	v_mfma_f32_16x16x32_bf16 v[40:43], v[160:163], v[184:187], v[40:43]
	v_mfma_f32_16x16x32_bf16 v[32:35], v[152:155], v[192:195], v[32:35]
	v_mfma_f32_16x16x32_bf16 v[24:27], v[160:163], v[192:195], v[24:27]
	v_mfma_f32_16x16x32_bf16 v[16:19], v[152:155], v[200:203], v[16:19]
	v_mfma_f32_16x16x32_bf16 v[8:11], v[160:163], v[200:203], v[8:11]

	s_barrier
	s_add_u32 s54, s24, 0x80000
	s_addc_u32 s55, s25, 0
	s_add_i32 s56, s46, s31
	s_mov_b32 m0, s56
	s_nop 0

	global_load_lds_dwordx4 v172, s[54:55]
	s_add_i32 m0, s56, 0x2000
	s_nop 0

	global_load_lds_dwordx4 v174, s[54:55]
	s_waitcnt vmcnt(6)
	s_barrier

	v_mfma_f32_16x16x32_bf16 v[52:55], v[204:207], v[164:167], v[52:55]
	v_mfma_f32_16x16x32_bf16 v[44:47], v[222:225], v[164:167], v[44:47]
	v_mfma_f32_16x16x32_bf16 v[36:39], v[204:207], v[180:183], v[36:39]
	v_mfma_f32_16x16x32_bf16 v[28:31], v[222:225], v[180:183], v[28:31]
	v_mfma_f32_16x16x32_bf16 v[20:23], v[204:207], v[188:191], v[20:23]
	v_mfma_f32_16x16x32_bf16 v[12:15], v[222:225], v[188:191], v[12:15]
	v_mfma_f32_16x16x32_bf16 v[4:7], v[204:207], v[196:199], v[4:7]
	v_mfma_f32_16x16x32_bf16 v[0:3], v[222:225], v[196:199], v[0:3]
	v_mfma_f32_16x16x32_bf16 v[52:55], v[218:221], v[176:179], v[52:55]
	v_mfma_f32_16x16x32_bf16 v[44:47], v[226:229], v[176:179], v[44:47]
	v_mfma_f32_16x16x32_bf16 v[36:39], v[218:221], v[184:187], v[36:39]
	v_mfma_f32_16x16x32_bf16 v[28:31], v[226:229], v[184:187], v[28:31]
	v_mfma_f32_16x16x32_bf16 v[20:23], v[218:221], v[192:195], v[20:23]
	v_mfma_f32_16x16x32_bf16 v[12:15], v[226:229], v[192:195], v[12:15]
	v_mfma_f32_16x16x32_bf16 v[4:7], v[218:221], v[200:203], v[4:7]
	v_mfma_f32_16x16x32_bf16 v[0:3], v[226:229], v[200:203], v[0:3]

	s_add_i32 s54, 0, 0x18000

	s_barrier
	ds_read_b128 v[148:151], v143 offset:32768
	ds_read_b128 v[152:155], v143 offset:33792
	ds_read_b128 v[156:159], v143 offset:34816
	ds_read_b128 v[160:163], v143 offset:35840
	s_add_u32 s26, s26, 0x80000
	s_addc_u32 s27, s27, 0
	s_mov_b32 m0, s36

	ds_read_b128 v[164:167], v145 offset:32768
	ds_read_b128 v[176:179], v145 offset:33792
	ds_read_b128 v[180:183], v145 offset:34816
	ds_read_b128 v[184:187], v145 offset:35840
	ds_read_b128 v[188:191], v145 offset:36864
	ds_read_b128 v[192:195], v145 offset:37888
	ds_read_b128 v[196:199], v145 offset:38912
	ds_read_b128 v[200:203], v145 offset:39936
	global_load_lds_dwordx4 v172, s[26:27]
	s_mov_b32 m0, s37
	s_nop 0

	global_load_lds_dwordx4 v174, s[26:27]
	s_waitcnt lgkmcnt(8)
	s_barrier
	s_waitcnt lgkmcnt(0)


	v_mfma_f32_16x16x32_bf16 v[124:127], v[148:151], v[164:167], v[124:127]
	v_mfma_f32_16x16x32_bf16 v[120:123], v[156:159], v[164:167], v[120:123]
	v_mfma_f32_16x16x32_bf16 v[116:119], v[148:151], v[180:183], v[116:119]
	v_mfma_f32_16x16x32_bf16 v[104:107], v[156:159], v[180:183], v[104:107]
	v_mfma_f32_16x16x32_bf16 v[96:99], v[148:151], v[188:191], v[96:99]
	v_mfma_f32_16x16x32_bf16 v[88:91], v[156:159], v[188:191], v[88:91]
	v_mfma_f32_16x16x32_bf16 v[80:83], v[148:151], v[196:199], v[80:83]
	v_mfma_f32_16x16x32_bf16 v[72:75], v[156:159], v[196:199], v[72:75]
	v_mfma_f32_16x16x32_bf16 v[124:127], v[152:155], v[176:179], v[124:127]
	v_mfma_f32_16x16x32_bf16 v[120:123], v[160:163], v[176:179], v[120:123]
	v_mfma_f32_16x16x32_bf16 v[116:119], v[152:155], v[184:187], v[116:119]
	v_mfma_f32_16x16x32_bf16 v[104:107], v[160:163], v[184:187], v[104:107]
	v_mfma_f32_16x16x32_bf16 v[96:99], v[152:155], v[192:195], v[96:99]
	v_mfma_f32_16x16x32_bf16 v[88:91], v[160:163], v[192:195], v[88:91]
	v_mfma_f32_16x16x32_bf16 v[80:83], v[152:155], v[200:203], v[80:83]
	v_mfma_f32_16x16x32_bf16 v[72:75], v[160:163], v[200:203], v[72:75]

	s_barrier
	s_add_i32 s26, 0, 0x1c000
	s_add_i32 s27, s54, s31


	s_mov_b32 m0, s27
	ds_read_b128 v[204:207], v147 offset:32768
	ds_read_b128 v[218:221], v147 offset:33792
	ds_read_b128 v[222:225], v147 offset:34816
	ds_read_b128 v[226:229], v147 offset:35840
	global_load_lds_dwordx4 v172, s[66:67]
	s_add_i32 m0, s27, 0x2000
	s_nop 0

	global_load_lds_dwordx4 v174, s[66:67]
	s_barrier
	s_waitcnt lgkmcnt(0)


	v_mfma_f32_16x16x32_bf16 v[112:115], v[204:207], v[164:167], v[112:115]
	v_mfma_f32_16x16x32_bf16 v[108:111], v[222:225], v[164:167], v[108:111]
	v_mfma_f32_16x16x32_bf16 v[100:103], v[204:207], v[180:183], v[100:103]
	v_mfma_f32_16x16x32_bf16 v[92:95], v[222:225], v[180:183], v[92:95]
	v_mfma_f32_16x16x32_bf16 v[84:87], v[204:207], v[188:191], v[84:87]
	v_mfma_f32_16x16x32_bf16 v[76:79], v[222:225], v[188:191], v[76:79]
	v_mfma_f32_16x16x32_bf16 v[68:71], v[204:207], v[196:199], v[68:71]
	v_mfma_f32_16x16x32_bf16 v[64:67], v[222:225], v[196:199], v[64:67]
	v_mfma_f32_16x16x32_bf16 v[112:115], v[218:221], v[176:179], v[112:115]
	v_mfma_f32_16x16x32_bf16 v[108:111], v[226:229], v[176:179], v[108:111]
	v_mfma_f32_16x16x32_bf16 v[100:103], v[218:221], v[184:187], v[100:103]
	v_mfma_f32_16x16x32_bf16 v[92:95], v[226:229], v[184:187], v[92:95]
	v_mfma_f32_16x16x32_bf16 v[84:87], v[218:221], v[192:195], v[84:87]
	v_mfma_f32_16x16x32_bf16 v[76:79], v[226:229], v[192:195], v[76:79]
	v_mfma_f32_16x16x32_bf16 v[68:71], v[218:221], v[200:203], v[68:71]
	v_mfma_f32_16x16x32_bf16 v[64:67], v[226:229], v[200:203], v[64:67]

	s_mov_b32 m0, s41

	s_barrier
	ds_read_b128 v[164:167], v145 offset:49152
	ds_read_b128 v[176:179], v145 offset:50176
	ds_read_b128 v[180:183], v145 offset:51200
	ds_read_b128 v[184:187], v145 offset:52224
	ds_read_b128 v[188:191], v145 offset:53248
	ds_read_b128 v[192:195], v145 offset:54272
	ds_read_b128 v[196:199], v145 offset:55296
	ds_read_b128 v[200:203], v145 offset:56320
	global_load_lds_dwordx4 v172, s[68:69]
	s_mov_b32 m0, s42
	s_nop 0

	global_load_lds_dwordx4 v174, s[68:69]
	s_barrier
	s_waitcnt lgkmcnt(0)


	v_mfma_f32_16x16x32_bf16 v[60:63], v[148:151], v[164:167], v[60:63]
	v_mfma_f32_16x16x32_bf16 v[56:59], v[156:159], v[164:167], v[56:59]
	v_mfma_f32_16x16x32_bf16 v[48:51], v[148:151], v[180:183], v[48:51]
	v_mfma_f32_16x16x32_bf16 v[40:43], v[156:159], v[180:183], v[40:43]
	v_mfma_f32_16x16x32_bf16 v[32:35], v[148:151], v[188:191], v[32:35]
	v_mfma_f32_16x16x32_bf16 v[24:27], v[156:159], v[188:191], v[24:27]
	v_mfma_f32_16x16x32_bf16 v[16:19], v[148:151], v[196:199], v[16:19]
	v_mfma_f32_16x16x32_bf16 v[8:11], v[156:159], v[196:199], v[8:11]
	v_mfma_f32_16x16x32_bf16 v[60:63], v[152:155], v[176:179], v[60:63]
	v_mfma_f32_16x16x32_bf16 v[56:59], v[160:163], v[176:179], v[56:59]
	v_mfma_f32_16x16x32_bf16 v[48:51], v[152:155], v[184:187], v[48:51]
	v_mfma_f32_16x16x32_bf16 v[40:43], v[160:163], v[184:187], v[40:43]
	v_mfma_f32_16x16x32_bf16 v[32:35], v[152:155], v[192:195], v[32:35]
	v_mfma_f32_16x16x32_bf16 v[24:27], v[160:163], v[192:195], v[24:27]
	v_mfma_f32_16x16x32_bf16 v[16:19], v[152:155], v[200:203], v[16:19]
	v_mfma_f32_16x16x32_bf16 v[8:11], v[160:163], v[200:203], v[8:11]

	s_barrier
	s_add_u32 s24, s24, 0x80080
	s_addc_u32 s25, s25, 0
	s_add_i32 s26, s26, s31
	s_mov_b32 m0, s26
	s_add_i32 s53, s53, 2

	global_load_lds_dwordx4 v172, s[24:25]
	s_add_i32 m0, s26, 0x2000
	s_add_u32 s22, s22, 0x100
	s_addc_u32 s23, s23, 0

	global_load_lds_dwordx4 v174, s[24:25]
	s_add_u32 s51, s51, 0x100
	s_addc_u32 s52, s52, 0
	s_waitcnt vmcnt(6)
	s_barrier

	v_mfma_f32_16x16x32_bf16 v[52:55], v[204:207], v[164:167], v[52:55]
	v_mfma_f32_16x16x32_bf16 v[44:47], v[222:225], v[164:167], v[44:47]
	v_mfma_f32_16x16x32_bf16 v[36:39], v[204:207], v[180:183], v[36:39]
	v_mfma_f32_16x16x32_bf16 v[28:31], v[222:225], v[180:183], v[28:31]
	v_mfma_f32_16x16x32_bf16 v[20:23], v[204:207], v[188:191], v[20:23]
	v_mfma_f32_16x16x32_bf16 v[12:15], v[222:225], v[188:191], v[12:15]
	v_mfma_f32_16x16x32_bf16 v[4:7], v[204:207], v[196:199], v[4:7]
	v_mfma_f32_16x16x32_bf16 v[0:3], v[222:225], v[196:199], v[0:3]
	v_mfma_f32_16x16x32_bf16 v[52:55], v[218:221], v[176:179], v[52:55]
	v_mfma_f32_16x16x32_bf16 v[44:47], v[226:229], v[176:179], v[44:47]
	v_mfma_f32_16x16x32_bf16 v[36:39], v[218:221], v[184:187], v[36:39]
	v_mfma_f32_16x16x32_bf16 v[28:31], v[226:229], v[184:187], v[28:31]
	v_mfma_f32_16x16x32_bf16 v[20:23], v[218:221], v[192:195], v[20:23]
	v_mfma_f32_16x16x32_bf16 v[12:15], v[226:229], v[192:195], v[12:15]
	v_mfma_f32_16x16x32_bf16 v[4:7], v[218:221], v[200:203], v[4:7]
	v_mfma_f32_16x16x32_bf16 v[0:3], v[226:229], v[200:203], v[0:3]


	s_cmp_gt_u32 s53, 29
	s_barrier
	s_cbranch_scc0 .LBB0_1167
	s_lshl_b32 s13, s20, 8
	v_mov_b32_e32 v138, v210
	v_mov_b32_e32 v142, v169
	s_add_i32 s13, s13, s39
	s_lshl_b32 s15, s48, 7
	v_add_u32_e32 v136, s13, v142
	v_ashrrev_i32_e32 v137, 31, v136
	v_lshl_add_u64 v[140:141], v[136:137], 2, s[2:3]
	global_load_dword v154, v[140:141], off
	global_load_dword v152, v[140:141], off offset:64
	v_lshl_add_u32 v138, v138, 4, v142
	v_and_b32_e32 v142, 3, v142
	v_ashrrev_i32_e32 v144, 2, v138
	v_and_b32_e32 v138, -4, v138
	v_lshl_or_b32 v146, v142, 2, s15
	v_add_u32_e32 v151, s13, v144
	v_lshl_add_u32 v149, v142, 6, v138
	v_or_b32_e32 v156, s40, v146
	global_load_dword v150, v[140:141], off offset:128
	global_load_dword v148, v[140:141], off offset:192
	global_load_dword v146, v[140:141], off offset:512
	global_load_dword v144, v[140:141], off offset:576
	global_load_dword v142, v[140:141], off offset:640
	global_load_dword v138, v[140:141], off offset:704
	v_mov_b64_e32 v[136:137], s[0:1]
	v_ashrrev_i32_e32 v157, 31, v156
	v_mad_i64_i32 v[158:159], s[22:23], v151, s47, v[136:137]
	v_lshlrev_b64 v[140:141], 1, v[156:157]
	v_lshl_add_u64 v[156:157], v[158:159], 0, v[140:141]
	v_add_u32_e32 v153, 16, v151
	s_and_b64 vcc, exec, s[4:5]
	s_mov_b32 s48, s12
	s_mov_b32 s20, s14
	s_mov_b64 s[24:25], s[18:19]
	s_waitcnt vmcnt(0)
	v_pk_mul_f32 v[126:127], v[126:127], v[154:155] op_sel_hi:[1,0]
	v_pk_mul_f32 v[124:125], v[124:125], v[154:155] op_sel_hi:[1,0]
	v_pk_mul_f32 v[114:115], v[114:115], v[154:155] op_sel_hi:[1,0]
	v_pk_mul_f32 v[112:113], v[112:113], v[154:155] op_sel_hi:[1,0]
	v_pk_mul_f32 v[122:123], v[122:123], v[154:155] op_sel_hi:[1,0]
	v_pk_mul_f32 v[120:121], v[120:121], v[154:155] op_sel_hi:[1,0]
	v_pk_mul_f32 v[110:111], v[110:111], v[154:155] op_sel_hi:[1,0]
	v_pk_mul_f32 v[108:109], v[108:109], v[154:155] op_sel_hi:[1,0]
	v_mul_f32_e32 v154, 0xbfb8aa3b, v124
	v_mul_f32_e32 v155, 0xbfb8aa3b, v125
	v_mul_f32_e32 v158, 0xbfb8aa3b, v126
	v_mul_f32_e32 v159, 0xbfb8aa3b, v127
	v_mul_f32_e32 v160, 0xbfb8aa3b, v120
	v_mul_f32_e32 v161, 0xbfb8aa3b, v121
	v_mul_f32_e32 v162, 0xbfb8aa3b, v122
	v_mul_f32_e32 v163, 0xbfb8aa3b, v123
	v_exp_f32_e32 v154, v154
	v_exp_f32_e32 v155, v155
	v_exp_f32_e32 v158, v158
	v_exp_f32_e32 v159, v159
	v_exp_f32_e32 v160, v160
	v_exp_f32_e32 v161, v161
	v_exp_f32_e32 v162, v162
	v_exp_f32_e32 v163, v163
	v_add_f32_e32 v154, 1.0, v154
	v_add_f32_e32 v155, 1.0, v155
	v_add_f32_e32 v158, 1.0, v158
	v_add_f32_e32 v159, 1.0, v159
	v_add_f32_e32 v160, 1.0, v160
	v_add_f32_e32 v161, 1.0, v161
	v_add_f32_e32 v162, 1.0, v162
	v_add_f32_e32 v163, 1.0, v163
	v_rcp_f32_e32 v154, v154
	v_rcp_f32_e32 v155, v155
	v_rcp_f32_e32 v158, v158
	v_rcp_f32_e32 v159, v159
	v_rcp_f32_e32 v160, v160
	v_rcp_f32_e32 v161, v161
	v_rcp_f32_e32 v162, v162
	v_rcp_f32_e32 v163, v163
	v_pk_mul_f32 v[124:125], v[124:125], v[154:155]
	v_pk_mul_f32 v[126:127], v[126:127], v[158:159]
	v_pk_mul_f32 v[120:121], v[120:121], v[160:161]
	v_pk_mul_f32 v[122:123], v[122:123], v[162:163]
	v_pk_mul_f32 v[112:113], v[112:113], v[124:125]
	v_pk_mul_f32 v[114:115], v[114:115], v[126:127]
	v_pk_mul_f32 v[118:119], v[118:119], v[152:153] op_sel_hi:[1,0]
	v_pk_mul_f32 v[116:117], v[116:117], v[152:153] op_sel_hi:[1,0]
	v_pk_mul_f32 v[108:109], v[108:109], v[120:121]
	v_pk_mul_f32 v[110:111], v[110:111], v[122:123]
	v_cvt_pk_bf16_f32 v112, v112, v113
	v_cvt_pk_bf16_f32 v113, v114, v115
	v_mul_f32_e32 v164, 0xbfb8aa3b, v116
	v_mul_f32_e32 v165, 0xbfb8aa3b, v117
	v_mul_f32_e32 v166, 0xbfb8aa3b, v118
	v_mul_f32_e32 v167, 0xbfb8aa3b, v119
	v_cvt_pk_bf16_f32 v114, v108, v109
	v_cvt_pk_bf16_f32 v111, v110, v111
	ds_bpermute_b32 v108, v149, v112
	ds_bpermute_b32 v109, v149, v113
	v_exp_f32_e32 v164, v164
	v_exp_f32_e32 v165, v165
	v_exp_f32_e32 v166, v166
	v_exp_f32_e32 v167, v167
	ds_bpermute_b32 v110, v149, v114
	ds_bpermute_b32 v111, v149, v111
	v_add_f32_e32 v164, 1.0, v164
	v_add_f32_e32 v113, 1.0, v165
	s_waitcnt lgkmcnt(0)
	global_store_dwordx2 v[156:157], v[108:109], off
	global_store_dwordx2 v[156:157], v[110:111], off offset:32
	v_add_f32_e32 v108, 1.0, v166
	v_add_f32_e32 v109, 1.0, v167
	v_rcp_f32_e32 v112, v164
	v_rcp_f32_e32 v113, v113
	v_rcp_f32_e32 v108, v108
	v_rcp_f32_e32 v109, v109
	v_pk_mul_f32 v[102:103], v[102:103], v[152:153] op_sel_hi:[1,0]
	v_pk_mul_f32 v[100:101], v[100:101], v[152:153] op_sel_hi:[1,0]
	v_pk_mul_f32 v[110:111], v[116:117], v[112:113]
	v_pk_mul_f32 v[108:109], v[118:119], v[108:109]
	v_pk_mul_f32 v[100:101], v[100:101], v[110:111]
	v_pk_mul_f32 v[102:103], v[102:103], v[108:109]
	v_cvt_pk_bf16_f32 v100, v100, v101
	v_cvt_pk_bf16_f32 v101, v102, v103
	v_pk_mul_f32 v[102:103], v[106:107], v[152:153] op_sel_hi:[1,0]
	v_pk_mul_f32 v[104:105], v[104:105], v[152:153] op_sel_hi:[1,0]
	v_mul_f32_e32 v108, 0xbfb8aa3b, v102
	v_mul_f32_e32 v106, 0xbfb8aa3b, v104
	v_mul_f32_e32 v107, 0xbfb8aa3b, v105
	v_mul_f32_e32 v109, 0xbfb8aa3b, v103
	v_exp_f32_e32 v106, v106
	v_exp_f32_e32 v107, v107
	v_exp_f32_e32 v108, v108
	v_exp_f32_e32 v109, v109
	v_add_f32_e32 v106, 1.0, v106
	v_add_f32_e32 v107, 1.0, v107
	v_add_f32_e32 v108, 1.0, v108
	v_add_f32_e32 v109, 1.0, v109
	v_rcp_f32_e32 v106, v106
	v_rcp_f32_e32 v107, v107
	v_rcp_f32_e32 v108, v108
	v_rcp_f32_e32 v109, v109
	v_pk_mul_f32 v[94:95], v[94:95], v[152:153] op_sel_hi:[1,0]
	v_pk_mul_f32 v[92:93], v[92:93], v[152:153] op_sel_hi:[1,0]
	v_pk_mul_f32 v[104:105], v[104:105], v[106:107]
	v_pk_mul_f32 v[102:103], v[102:103], v[108:109]
	v_pk_mul_f32 v[92:93], v[92:93], v[104:105]
	v_pk_mul_f32 v[94:95], v[94:95], v[102:103]
	ds_bpermute_b32 v100, v149, v100
	ds_bpermute_b32 v101, v149, v101
	v_cvt_pk_bf16_f32 v92, v92, v93
	v_cvt_pk_bf16_f32 v93, v94, v95
	ds_bpermute_b32 v92, v149, v92
	ds_bpermute_b32 v93, v149, v93
	v_mad_i64_i32 v[94:95], s[22:23], v153, s47, v[136:137]
	v_lshl_add_u64 v[94:95], v[94:95], 0, v[140:141]
	s_waitcnt lgkmcnt(2)
	global_store_dwordx2 v[94:95], v[100:101], off
	s_waitcnt lgkmcnt(0)
	global_store_dwordx2 v[94:95], v[92:93], off offset:32
	v_pk_mul_f32 v[92:93], v[98:99], v[150:151] op_sel_hi:[1,0]
	v_pk_mul_f32 v[94:95], v[96:97], v[150:151] op_sel_hi:[1,0]
	v_mul_f32_e32 v98, 0xbfb8aa3b, v92
	v_mul_f32_e32 v96, 0xbfb8aa3b, v94
	v_mul_f32_e32 v97, 0xbfb8aa3b, v95
	v_mul_f32_e32 v99, 0xbfb8aa3b, v93
	v_exp_f32_e32 v96, v96
	v_exp_f32_e32 v97, v97
	v_exp_f32_e32 v98, v98
	v_exp_f32_e32 v99, v99
	v_add_f32_e32 v96, 1.0, v96
	v_add_f32_e32 v97, 1.0, v97
	v_add_f32_e32 v98, 1.0, v98
	v_add_f32_e32 v99, 1.0, v99
	v_rcp_f32_e32 v96, v96
	v_rcp_f32_e32 v97, v97
	v_rcp_f32_e32 v98, v98
	v_rcp_f32_e32 v99, v99
	v_pk_mul_f32 v[86:87], v[86:87], v[150:151] op_sel_hi:[1,0]
	v_pk_mul_f32 v[84:85], v[84:85], v[150:151] op_sel_hi:[1,0]
	v_pk_mul_f32 v[94:95], v[94:95], v[96:97]
	v_pk_mul_f32 v[92:93], v[92:93], v[98:99]
	v_pk_mul_f32 v[84:85], v[84:85], v[94:95]
	v_pk_mul_f32 v[86:87], v[86:87], v[92:93]
	v_cvt_pk_bf16_f32 v84, v84, v85
	v_cvt_pk_bf16_f32 v85, v86, v87
	v_pk_mul_f32 v[86:87], v[90:91], v[150:151] op_sel_hi:[1,0]
	v_pk_mul_f32 v[88:89], v[88:89], v[150:151] op_sel_hi:[1,0]
	v_mul_f32_e32 v92, 0xbfb8aa3b, v86
	v_mul_f32_e32 v90, 0xbfb8aa3b, v88
	v_mul_f32_e32 v91, 0xbfb8aa3b, v89
	v_mul_f32_e32 v93, 0xbfb8aa3b, v87
	v_exp_f32_e32 v90, v90
	v_exp_f32_e32 v91, v91
	v_exp_f32_e32 v92, v92
	v_exp_f32_e32 v93, v93
	v_add_f32_e32 v90, 1.0, v90
	v_add_f32_e32 v91, 1.0, v91
	v_add_f32_e32 v92, 1.0, v92
	v_add_f32_e32 v93, 1.0, v93
	v_rcp_f32_e32 v90, v90
	v_rcp_f32_e32 v91, v91
	v_rcp_f32_e32 v92, v92
	v_rcp_f32_e32 v93, v93
	v_pk_mul_f32 v[78:79], v[78:79], v[150:151] op_sel_hi:[1,0]
	v_pk_mul_f32 v[76:77], v[76:77], v[150:151] op_sel_hi:[1,0]
	v_pk_mul_f32 v[88:89], v[88:89], v[90:91]
	v_pk_mul_f32 v[86:87], v[86:87], v[92:93]
	v_pk_mul_f32 v[76:77], v[76:77], v[88:89]
	v_pk_mul_f32 v[78:79], v[78:79], v[86:87]
	ds_bpermute_b32 v84, v149, v84
	ds_bpermute_b32 v85, v149, v85
	v_cvt_pk_bf16_f32 v76, v76, v77
	v_cvt_pk_bf16_f32 v77, v78, v79
	ds_bpermute_b32 v76, v149, v76
	ds_bpermute_b32 v77, v149, v77
	v_add_u32_e32 v100, 32, v151
	v_mad_i64_i32 v[78:79], s[22:23], v100, s47, v[136:137]
	v_lshl_add_u64 v[78:79], v[78:79], 0, v[140:141]
	s_waitcnt lgkmcnt(2)
	global_store_dwordx2 v[78:79], v[84:85], off
	s_waitcnt lgkmcnt(0)
	global_store_dwordx2 v[78:79], v[76:77], off offset:32
	v_pk_mul_f32 v[76:77], v[82:83], v[148:149] op_sel_hi:[1,0]
	v_pk_mul_f32 v[78:79], v[80:81], v[148:149] op_sel_hi:[1,0]
	v_mul_f32_e32 v82, 0xbfb8aa3b, v76
	v_mul_f32_e32 v80, 0xbfb8aa3b, v78
	v_mul_f32_e32 v81, 0xbfb8aa3b, v79
	v_mul_f32_e32 v83, 0xbfb8aa3b, v77
	v_exp_f32_e32 v80, v80
	v_exp_f32_e32 v81, v81
	v_exp_f32_e32 v82, v82
	v_exp_f32_e32 v83, v83
	v_add_f32_e32 v80, 1.0, v80
	v_add_f32_e32 v81, 1.0, v81
	v_add_f32_e32 v82, 1.0, v82
	v_add_f32_e32 v83, 1.0, v83
	v_rcp_f32_e32 v80, v80
	v_rcp_f32_e32 v81, v81
	v_rcp_f32_e32 v82, v82
	v_rcp_f32_e32 v83, v83
	v_pk_mul_f32 v[70:71], v[70:71], v[148:149] op_sel_hi:[1,0]
	v_pk_mul_f32 v[68:69], v[68:69], v[148:149] op_sel_hi:[1,0]
	v_pk_mul_f32 v[78:79], v[78:79], v[80:81]
	v_pk_mul_f32 v[76:77], v[76:77], v[82:83]
	v_pk_mul_f32 v[68:69], v[68:69], v[78:79]
	v_pk_mul_f32 v[70:71], v[70:71], v[76:77]
	v_cvt_pk_bf16_f32 v68, v68, v69
	v_cvt_pk_bf16_f32 v69, v70, v71
	v_pk_mul_f32 v[70:71], v[74:75], v[148:149] op_sel_hi:[1,0]
	v_pk_mul_f32 v[72:73], v[72:73], v[148:149] op_sel_hi:[1,0]
	v_mul_f32_e32 v76, 0xbfb8aa3b, v70
	v_mul_f32_e32 v74, 0xbfb8aa3b, v72
	v_mul_f32_e32 v75, 0xbfb8aa3b, v73
	v_mul_f32_e32 v77, 0xbfb8aa3b, v71
	v_exp_f32_e32 v74, v74
	v_exp_f32_e32 v75, v75
	v_exp_f32_e32 v76, v76
	v_exp_f32_e32 v77, v77
	v_add_f32_e32 v74, 1.0, v74
	v_add_f32_e32 v75, 1.0, v75
	v_add_f32_e32 v76, 1.0, v76
	v_add_f32_e32 v77, 1.0, v77
	v_rcp_f32_e32 v74, v74
	v_rcp_f32_e32 v75, v75
	v_rcp_f32_e32 v76, v76
	v_rcp_f32_e32 v77, v77
	v_pk_mul_f32 v[66:67], v[66:67], v[148:149] op_sel_hi:[1,0]
	v_pk_mul_f32 v[64:65], v[64:65], v[148:149] op_sel_hi:[1,0]
	v_pk_mul_f32 v[72:73], v[72:73], v[74:75]
	v_pk_mul_f32 v[70:71], v[70:71], v[76:77]
	v_pk_mul_f32 v[64:65], v[64:65], v[72:73]
	v_pk_mul_f32 v[66:67], v[66:67], v[70:71]
	ds_bpermute_b32 v68, v149, v68
	ds_bpermute_b32 v69, v149, v69
	v_cvt_pk_bf16_f32 v64, v64, v65
	v_cvt_pk_bf16_f32 v65, v66, v67
	ds_bpermute_b32 v64, v149, v64
	ds_bpermute_b32 v65, v149, v65
	v_add_u32_e32 v84, 48, v151
	v_mad_i64_i32 v[66:67], s[22:23], v84, s47, v[136:137]
	v_lshl_add_u64 v[66:67], v[66:67], 0, v[140:141]
	v_pk_mul_f32 v[60:61], v[60:61], v[146:147] op_sel_hi:[1,0]
	s_waitcnt lgkmcnt(2)
	global_store_dwordx2 v[66:67], v[68:69], off
	s_waitcnt lgkmcnt(0)
	global_store_dwordx2 v[66:67], v[64:65], off offset:32
	v_pk_mul_f32 v[62:63], v[62:63], v[146:147] op_sel_hi:[1,0]
	v_mul_f32_e32 v64, 0xbfb8aa3b, v60
	v_mul_f32_e32 v65, 0xbfb8aa3b, v61
	v_exp_f32_e32 v64, v64
	v_exp_f32_e32 v65, v65
	v_mul_f32_e32 v66, 0xbfb8aa3b, v62
	v_mul_f32_e32 v67, 0xbfb8aa3b, v63
	v_exp_f32_e32 v66, v66
	v_exp_f32_e32 v67, v67
	v_add_f32_e32 v64, 1.0, v64
	v_add_f32_e32 v65, 1.0, v65
	v_rcp_f32_e32 v64, v64
	v_rcp_f32_e32 v65, v65
	v_add_f32_e32 v66, 1.0, v66
	v_add_f32_e32 v67, 1.0, v67
	v_rcp_f32_e32 v66, v66
	v_rcp_f32_e32 v67, v67
	v_pk_mul_f32 v[52:53], v[52:53], v[146:147] op_sel_hi:[1,0]
	v_pk_mul_f32 v[60:61], v[60:61], v[64:65]
	v_pk_mul_f32 v[54:55], v[54:55], v[146:147] op_sel_hi:[1,0]
	v_pk_mul_f32 v[52:53], v[52:53], v[60:61]
	v_pk_mul_f32 v[60:61], v[62:63], v[66:67]
	v_cvt_pk_bf16_f32 v52, v52, v53
	v_pk_mul_f32 v[54:55], v[54:55], v[60:61]
	v_pk_mul_f32 v[56:57], v[56:57], v[146:147] op_sel_hi:[1,0]
	v_cvt_pk_bf16_f32 v53, v54, v55
	v_pk_mul_f32 v[54:55], v[58:59], v[146:147] op_sel_hi:[1,0]
	v_mul_f32_e32 v58, 0xbfb8aa3b, v56
	v_mul_f32_e32 v59, 0xbfb8aa3b, v57
	v_mul_f32_e32 v60, 0xbfb8aa3b, v54
	v_mul_f32_e32 v61, 0xbfb8aa3b, v55
	v_exp_f32_e32 v58, v58
	v_exp_f32_e32 v59, v59
	v_exp_f32_e32 v60, v60
	v_exp_f32_e32 v61, v61
	v_add_f32_e32 v58, 1.0, v58
	v_add_f32_e32 v59, 1.0, v59
	v_add_f32_e32 v60, 1.0, v60
	v_add_f32_e32 v61, 1.0, v61
	v_rcp_f32_e32 v58, v58
	v_rcp_f32_e32 v59, v59
	v_rcp_f32_e32 v60, v60
	v_rcp_f32_e32 v61, v61
	v_pk_mul_f32 v[46:47], v[46:47], v[146:147] op_sel_hi:[1,0]
	v_pk_mul_f32 v[44:45], v[44:45], v[146:147] op_sel_hi:[1,0]
	v_pk_mul_f32 v[56:57], v[56:57], v[58:59]
	v_pk_mul_f32 v[54:55], v[54:55], v[60:61]
	v_pk_mul_f32 v[44:45], v[44:45], v[56:57]
	v_pk_mul_f32 v[46:47], v[46:47], v[54:55]
	ds_bpermute_b32 v52, v149, v52
	ds_bpermute_b32 v53, v149, v53
	v_cvt_pk_bf16_f32 v44, v44, v45
	v_cvt_pk_bf16_f32 v45, v46, v47
	ds_bpermute_b32 v44, v149, v44
	ds_bpermute_b32 v45, v149, v45
	v_add_u32_e32 v68, 0x80, v151
	v_mad_i64_i32 v[46:47], s[22:23], v68, s47, v[136:137]
	v_lshl_add_u64 v[46:47], v[46:47], 0, v[140:141]
	s_waitcnt lgkmcnt(2)
	global_store_dwordx2 v[46:47], v[52:53], off
	s_waitcnt lgkmcnt(0)
	global_store_dwordx2 v[46:47], v[44:45], off offset:32
	v_pk_mul_f32 v[44:45], v[50:51], v[144:145] op_sel_hi:[1,0]
	v_pk_mul_f32 v[46:47], v[48:49], v[144:145] op_sel_hi:[1,0]
	v_mul_f32_e32 v50, 0xbfb8aa3b, v44
	v_mul_f32_e32 v48, 0xbfb8aa3b, v46
	v_mul_f32_e32 v49, 0xbfb8aa3b, v47
	v_mul_f32_e32 v51, 0xbfb8aa3b, v45
	v_exp_f32_e32 v48, v48
	v_exp_f32_e32 v49, v49
	v_exp_f32_e32 v50, v50
	v_exp_f32_e32 v51, v51
	v_add_f32_e32 v48, 1.0, v48
	v_add_f32_e32 v49, 1.0, v49
	v_add_f32_e32 v50, 1.0, v50
	v_add_f32_e32 v51, 1.0, v51
	v_rcp_f32_e32 v48, v48
	v_rcp_f32_e32 v49, v49
	v_rcp_f32_e32 v50, v50
	v_rcp_f32_e32 v51, v51
	v_pk_mul_f32 v[38:39], v[38:39], v[144:145] op_sel_hi:[1,0]
	v_pk_mul_f32 v[36:37], v[36:37], v[144:145] op_sel_hi:[1,0]
	v_pk_mul_f32 v[46:47], v[46:47], v[48:49]
	v_pk_mul_f32 v[44:45], v[44:45], v[50:51]
	v_pk_mul_f32 v[36:37], v[36:37], v[46:47]
	v_pk_mul_f32 v[38:39], v[38:39], v[44:45]
	v_cvt_pk_bf16_f32 v36, v36, v37
	v_cvt_pk_bf16_f32 v37, v38, v39
	v_pk_mul_f32 v[38:39], v[42:43], v[144:145] op_sel_hi:[1,0]
	v_pk_mul_f32 v[40:41], v[40:41], v[144:145] op_sel_hi:[1,0]
	v_mul_f32_e32 v44, 0xbfb8aa3b, v38
	v_mul_f32_e32 v42, 0xbfb8aa3b, v40
	v_mul_f32_e32 v43, 0xbfb8aa3b, v41
	v_mul_f32_e32 v45, 0xbfb8aa3b, v39
	v_exp_f32_e32 v42, v42
	v_exp_f32_e32 v43, v43
	v_exp_f32_e32 v44, v44
	v_exp_f32_e32 v45, v45
	v_add_f32_e32 v42, 1.0, v42
	v_add_f32_e32 v43, 1.0, v43
	v_add_f32_e32 v44, 1.0, v44
	v_add_f32_e32 v45, 1.0, v45
	v_rcp_f32_e32 v42, v42
	v_rcp_f32_e32 v43, v43
	v_rcp_f32_e32 v44, v44
	v_rcp_f32_e32 v45, v45
	v_pk_mul_f32 v[30:31], v[30:31], v[144:145] op_sel_hi:[1,0]
	v_pk_mul_f32 v[28:29], v[28:29], v[144:145] op_sel_hi:[1,0]
	v_pk_mul_f32 v[40:41], v[40:41], v[42:43]
	v_pk_mul_f32 v[38:39], v[38:39], v[44:45]
	v_pk_mul_f32 v[28:29], v[28:29], v[40:41]
	v_pk_mul_f32 v[30:31], v[30:31], v[38:39]
	ds_bpermute_b32 v36, v149, v36
	ds_bpermute_b32 v37, v149, v37
	v_cvt_pk_bf16_f32 v28, v28, v29
	v_cvt_pk_bf16_f32 v29, v30, v31
	ds_bpermute_b32 v28, v149, v28
	ds_bpermute_b32 v29, v149, v29
	v_add_u32_e32 v52, 0x90, v151
	v_mad_i64_i32 v[30:31], s[22:23], v52, s47, v[136:137]
	v_lshl_add_u64 v[30:31], v[30:31], 0, v[140:141]
	s_waitcnt lgkmcnt(2)
	global_store_dwordx2 v[30:31], v[36:37], off
	s_waitcnt lgkmcnt(0)
	global_store_dwordx2 v[30:31], v[28:29], off offset:32
	v_pk_mul_f32 v[28:29], v[34:35], v[142:143] op_sel_hi:[1,0]
	v_pk_mul_f32 v[30:31], v[32:33], v[142:143] op_sel_hi:[1,0]
	v_mul_f32_e32 v34, 0xbfb8aa3b, v28
	v_mul_f32_e32 v32, 0xbfb8aa3b, v30
	v_mul_f32_e32 v33, 0xbfb8aa3b, v31
	v_mul_f32_e32 v35, 0xbfb8aa3b, v29
	v_exp_f32_e32 v32, v32
	v_exp_f32_e32 v33, v33
	v_exp_f32_e32 v34, v34
	v_exp_f32_e32 v35, v35
	v_add_f32_e32 v32, 1.0, v32
	v_add_f32_e32 v33, 1.0, v33
	v_add_f32_e32 v34, 1.0, v34
	v_add_f32_e32 v35, 1.0, v35
	v_rcp_f32_e32 v32, v32
	v_rcp_f32_e32 v33, v33
	v_rcp_f32_e32 v34, v34
	v_rcp_f32_e32 v35, v35
	v_pk_mul_f32 v[22:23], v[22:23], v[142:143] op_sel_hi:[1,0]
	v_pk_mul_f32 v[20:21], v[20:21], v[142:143] op_sel_hi:[1,0]
	v_pk_mul_f32 v[30:31], v[30:31], v[32:33]
	v_pk_mul_f32 v[28:29], v[28:29], v[34:35]
	v_pk_mul_f32 v[20:21], v[20:21], v[30:31]
	v_pk_mul_f32 v[22:23], v[22:23], v[28:29]
	v_cvt_pk_bf16_f32 v20, v20, v21
	v_cvt_pk_bf16_f32 v21, v22, v23
	v_pk_mul_f32 v[22:23], v[26:27], v[142:143] op_sel_hi:[1,0]
	v_pk_mul_f32 v[24:25], v[24:25], v[142:143] op_sel_hi:[1,0]
	v_mul_f32_e32 v28, 0xbfb8aa3b, v22
	v_mul_f32_e32 v26, 0xbfb8aa3b, v24
	v_mul_f32_e32 v27, 0xbfb8aa3b, v25
	v_mul_f32_e32 v29, 0xbfb8aa3b, v23
	v_exp_f32_e32 v26, v26
	v_exp_f32_e32 v27, v27
	v_exp_f32_e32 v28, v28
	v_exp_f32_e32 v29, v29
	v_add_f32_e32 v26, 1.0, v26
	v_add_f32_e32 v27, 1.0, v27
	v_add_f32_e32 v28, 1.0, v28
	v_add_f32_e32 v29, 1.0, v29
	v_rcp_f32_e32 v26, v26
	v_rcp_f32_e32 v27, v27
	v_rcp_f32_e32 v28, v28
	v_rcp_f32_e32 v29, v29
	v_pk_mul_f32 v[14:15], v[14:15], v[142:143] op_sel_hi:[1,0]
	v_pk_mul_f32 v[12:13], v[12:13], v[142:143] op_sel_hi:[1,0]
	v_pk_mul_f32 v[24:25], v[24:25], v[26:27]
	v_pk_mul_f32 v[22:23], v[22:23], v[28:29]
	v_pk_mul_f32 v[12:13], v[12:13], v[24:25]
	v_pk_mul_f32 v[14:15], v[14:15], v[22:23]
	ds_bpermute_b32 v20, v149, v20
	ds_bpermute_b32 v21, v149, v21
	v_cvt_pk_bf16_f32 v12, v12, v13
	v_cvt_pk_bf16_f32 v13, v14, v15
	ds_bpermute_b32 v12, v149, v12
	ds_bpermute_b32 v13, v149, v13
	v_add_u32_e32 v36, 0xa0, v151
	v_mad_i64_i32 v[14:15], s[22:23], v36, s47, v[136:137]
	v_lshl_add_u64 v[14:15], v[14:15], 0, v[140:141]
	s_waitcnt lgkmcnt(2)
	global_store_dwordx2 v[14:15], v[20:21], off
	s_waitcnt lgkmcnt(0)
	global_store_dwordx2 v[14:15], v[12:13], off offset:32
	v_pk_mul_f32 v[12:13], v[18:19], v[138:139] op_sel_hi:[1,0]
	v_pk_mul_f32 v[14:15], v[16:17], v[138:139] op_sel_hi:[1,0]
	v_mul_f32_e32 v18, 0xbfb8aa3b, v12
	v_mul_f32_e32 v16, 0xbfb8aa3b, v14
	v_mul_f32_e32 v17, 0xbfb8aa3b, v15
	v_mul_f32_e32 v19, 0xbfb8aa3b, v13
	v_exp_f32_e32 v16, v16
	v_exp_f32_e32 v17, v17
	v_exp_f32_e32 v18, v18
	v_exp_f32_e32 v19, v19
	v_add_f32_e32 v16, 1.0, v16
	v_add_f32_e32 v17, 1.0, v17
	v_add_f32_e32 v18, 1.0, v18
	v_add_f32_e32 v19, 1.0, v19
	v_rcp_f32_e32 v16, v16
	v_rcp_f32_e32 v17, v17
	v_rcp_f32_e32 v18, v18
	v_rcp_f32_e32 v19, v19
	v_pk_mul_f32 v[6:7], v[6:7], v[138:139] op_sel_hi:[1,0]
	v_pk_mul_f32 v[4:5], v[4:5], v[138:139] op_sel_hi:[1,0]
	v_pk_mul_f32 v[14:15], v[14:15], v[16:17]
	v_pk_mul_f32 v[12:13], v[12:13], v[18:19]
	v_pk_mul_f32 v[4:5], v[4:5], v[14:15]
	v_pk_mul_f32 v[6:7], v[6:7], v[12:13]
	v_cvt_pk_bf16_f32 v4, v4, v5
	v_cvt_pk_bf16_f32 v5, v6, v7
	v_pk_mul_f32 v[6:7], v[10:11], v[138:139] op_sel_hi:[1,0]
	v_pk_mul_f32 v[8:9], v[8:9], v[138:139] op_sel_hi:[1,0]
	v_mul_f32_e32 v12, 0xbfb8aa3b, v6
	v_mul_f32_e32 v10, 0xbfb8aa3b, v8
	v_mul_f32_e32 v11, 0xbfb8aa3b, v9
	v_mul_f32_e32 v13, 0xbfb8aa3b, v7
	v_exp_f32_e32 v10, v10
	v_exp_f32_e32 v11, v11
	v_exp_f32_e32 v12, v12
	v_exp_f32_e32 v13, v13
	v_add_f32_e32 v10, 1.0, v10
	v_add_f32_e32 v11, 1.0, v11
	v_add_f32_e32 v12, 1.0, v12
	v_add_f32_e32 v13, 1.0, v13
	v_rcp_f32_e32 v10, v10
	v_rcp_f32_e32 v11, v11
	v_rcp_f32_e32 v12, v12
	v_rcp_f32_e32 v13, v13
	v_pk_mul_f32 v[2:3], v[2:3], v[138:139] op_sel_hi:[1,0]
	v_pk_mul_f32 v[0:1], v[0:1], v[138:139] op_sel_hi:[1,0]
	v_pk_mul_f32 v[8:9], v[8:9], v[10:11]
	v_pk_mul_f32 v[6:7], v[6:7], v[12:13]
	v_pk_mul_f32 v[0:1], v[0:1], v[8:9]
	v_pk_mul_f32 v[2:3], v[2:3], v[6:7]
	ds_bpermute_b32 v4, v149, v4
	ds_bpermute_b32 v5, v149, v5
	v_cvt_pk_bf16_f32 v0, v0, v1
	v_cvt_pk_bf16_f32 v1, v2, v3
	ds_bpermute_b32 v0, v149, v0
	ds_bpermute_b32 v1, v149, v1
	v_add_u32_e32 v20, 0xb0, v151
	v_mad_i64_i32 v[2:3], s[22:23], v20, s47, v[136:137]
	v_lshl_add_u64 v[2:3], v[2:3], 0, v[140:141]
	s_mov_b64 s[22:23], s[16:17]
	s_waitcnt lgkmcnt(2)
	global_store_dwordx2 v[2:3], v[4:5], off
	s_waitcnt lgkmcnt(0)
	global_store_dwordx2 v[2:3], v[0:1], off offset:32
	s_cbranch_vccz .LBB0_1164
	s_waitcnt vmcnt(0)
	s_cmpk_gt_u32 s28, 0xff
	s_cbranch_scc1 .LBB0_1171
	s_barrier

.LBB0_1258:
	ds_read_b128 v[128:131], v159
	ds_read_b128 v[132:135], v159 offset:1024
	ds_read_b128 v[136:139], v159 offset:2048
	ds_read_b128 v[150:153], v159 offset:3072
	s_add_i32 s54, s18, 2
	s_add_u32 s19, s16, 0xffea0080
	s_addc_u32 s20, s17, -1
	s_cmp_eq_u32 s13, s18
	s_cselect_b32 s18, s4, s52
	s_cselect_b32 s21, s15, s20
	s_cselect_b32 s20, s14, s19
	s_cselect_b32 s19, s5, s53

	s_add_i32 m0, s26, 0xc000
	ds_read_b128 v[154:157], v160
	ds_read_b128 v[162:165], v160 offset:1024
	ds_read_b128 v[172:175], v160 offset:2048
	ds_read_b128 v[176:179], v160 offset:3072
	ds_read_b128 v[180:183], v160 offset:4096
	ds_read_b128 v[184:187], v160 offset:5120
	ds_read_b128 v[188:191], v160 offset:6144
	ds_read_b128 v[192:195], v160 offset:7168
	global_load_lds_dwordx4 v146, s[16:17]
	s_add_i32 m0, s26, 0xe000
	s_nop 0

	global_load_lds_dwordx4 v148, s[16:17]
	s_waitcnt lgkmcnt(8)
	s_barrier
	s_waitcnt lgkmcnt(0)


	v_mfma_f32_16x16x32_bf16 v[124:127], v[128:131], v[154:157], v[124:127]
	v_mfma_f32_16x16x32_bf16 v[120:123], v[136:139], v[154:157], v[120:123]
	v_mfma_f32_16x16x32_bf16 v[116:119], v[128:131], v[172:175], v[116:119]
	v_mfma_f32_16x16x32_bf16 v[104:107], v[136:139], v[172:175], v[104:107]
	v_mfma_f32_16x16x32_bf16 v[96:99], v[128:131], v[180:183], v[96:99]
	v_mfma_f32_16x16x32_bf16 v[88:91], v[136:139], v[180:183], v[88:91]
	v_mfma_f32_16x16x32_bf16 v[80:83], v[128:131], v[188:191], v[80:83]
	v_mfma_f32_16x16x32_bf16 v[72:75], v[136:139], v[188:191], v[72:75]
	v_mfma_f32_16x16x32_bf16 v[124:127], v[132:135], v[162:165], v[124:127]
	v_mfma_f32_16x16x32_bf16 v[120:123], v[150:153], v[162:165], v[120:123]
	v_mfma_f32_16x16x32_bf16 v[116:119], v[132:135], v[176:179], v[116:119]
	v_mfma_f32_16x16x32_bf16 v[104:107], v[150:153], v[176:179], v[104:107]
	v_mfma_f32_16x16x32_bf16 v[96:99], v[132:135], v[184:187], v[96:99]
	v_mfma_f32_16x16x32_bf16 v[88:91], v[150:153], v[184:187], v[88:91]
	v_mfma_f32_16x16x32_bf16 v[80:83], v[132:135], v[192:195], v[80:83]
	v_mfma_f32_16x16x32_bf16 v[72:75], v[150:153], v[192:195], v[72:75]

	s_barrier
	s_add_i32 s55, s35, s25
	s_add_u32 s66, s18, s6
	s_addc_u32 s67, s19, s7
	s_mov_b32 m0, s55
	ds_read_b128 v[196:199], v161
	ds_read_b128 v[200:203], v161 offset:1024
	ds_read_b128 v[204:207], v161 offset:2048
	ds_read_b128 v[212:215], v161 offset:3072
	global_load_lds_dwordx4 v140, s[18:19]
	s_add_i32 m0, s55, 0x2000
	s_nop 0

	global_load_lds_dwordx4 v142, s[18:19]
	s_barrier
	s_waitcnt lgkmcnt(0)


	v_mfma_f32_16x16x32_bf16 v[112:115], v[196:199], v[154:157], v[112:115]
	v_mfma_f32_16x16x32_bf16 v[108:111], v[204:207], v[154:157], v[108:111]
	v_mfma_f32_16x16x32_bf16 v[100:103], v[196:199], v[172:175], v[100:103]
	v_mfma_f32_16x16x32_bf16 v[92:95], v[204:207], v[172:175], v[92:95]
	v_mfma_f32_16x16x32_bf16 v[84:87], v[196:199], v[180:183], v[84:87]
	v_mfma_f32_16x16x32_bf16 v[76:79], v[204:207], v[180:183], v[76:79]
	v_mfma_f32_16x16x32_bf16 v[68:71], v[196:199], v[188:191], v[68:71]
	v_mfma_f32_16x16x32_bf16 v[64:67], v[204:207], v[188:191], v[64:67]
	v_mfma_f32_16x16x32_bf16 v[112:115], v[200:203], v[162:165], v[112:115]
	v_mfma_f32_16x16x32_bf16 v[108:111], v[212:215], v[162:165], v[108:111]
	v_mfma_f32_16x16x32_bf16 v[100:103], v[200:203], v[176:179], v[100:103]
	v_mfma_f32_16x16x32_bf16 v[92:95], v[212:215], v[176:179], v[92:95]
	v_mfma_f32_16x16x32_bf16 v[84:87], v[200:203], v[184:187], v[84:87]
	v_mfma_f32_16x16x32_bf16 v[76:79], v[212:215], v[184:187], v[76:79]
	v_mfma_f32_16x16x32_bf16 v[68:71], v[200:203], v[192:195], v[68:71]
	v_mfma_f32_16x16x32_bf16 v[64:67], v[212:215], v[192:195], v[64:67]

	s_mov_b32 m0, s26
	s_add_u32 s68, s20, s6
	s_addc_u32 s69, s21, s7
	s_barrier
	ds_read_b128 v[154:157], v160 offset:16384
	ds_read_b128 v[162:165], v160 offset:17408
	ds_read_b128 v[172:175], v160 offset:18432
	ds_read_b128 v[176:179], v160 offset:19456
	ds_read_b128 v[180:183], v160 offset:20480
	ds_read_b128 v[184:187], v160 offset:21504
	ds_read_b128 v[188:191], v160 offset:22528
	ds_read_b128 v[192:195], v160 offset:23552
	global_load_lds_dwordx4 v140, s[20:21]
	s_mov_b32 m0, s27
	s_nop 0

	global_load_lds_dwordx4 v142, s[20:21]
	s_barrier
	s_waitcnt lgkmcnt(0)


	v_mfma_f32_16x16x32_bf16 v[60:63], v[128:131], v[154:157], v[60:63]
	v_mfma_f32_16x16x32_bf16 v[56:59], v[136:139], v[154:157], v[56:59]
	v_mfma_f32_16x16x32_bf16 v[52:55], v[128:131], v[172:175], v[52:55]
	v_mfma_f32_16x16x32_bf16 v[40:43], v[136:139], v[172:175], v[40:43]
	v_mfma_f32_16x16x32_bf16 v[36:39], v[128:131], v[180:183], v[36:39]
	v_mfma_f32_16x16x32_bf16 v[24:27], v[136:139], v[180:183], v[24:27]
	v_mfma_f32_16x16x32_bf16 v[20:23], v[128:131], v[188:191], v[20:23]
	v_mfma_f32_16x16x32_bf16 v[8:11], v[136:139], v[188:191], v[8:11]
	v_mfma_f32_16x16x32_bf16 v[60:63], v[132:135], v[162:165], v[60:63]
	v_mfma_f32_16x16x32_bf16 v[56:59], v[150:153], v[162:165], v[56:59]
	v_mfma_f32_16x16x32_bf16 v[52:55], v[132:135], v[176:179], v[52:55]
	v_mfma_f32_16x16x32_bf16 v[40:43], v[150:153], v[176:179], v[40:43]
	v_mfma_f32_16x16x32_bf16 v[36:39], v[132:135], v[184:187], v[36:39]
	v_mfma_f32_16x16x32_bf16 v[24:27], v[150:153], v[184:187], v[24:27]
	v_mfma_f32_16x16x32_bf16 v[20:23], v[132:135], v[192:195], v[20:23]
	v_mfma_f32_16x16x32_bf16 v[8:11], v[150:153], v[192:195], v[8:11]

	s_barrier
	s_add_u32 s56, s18, 0x160000
	s_addc_u32 s57, s19, 0
	s_add_i32 s55, s36, s25
	s_mov_b32 m0, s55
	s_nop 0

	global_load_lds_dwordx4 v140, s[56:57]
	s_add_i32 m0, s55, 0x2000
	s_nop 0

	global_load_lds_dwordx4 v142, s[56:57]
	s_waitcnt vmcnt(6)
	s_barrier

	v_mfma_f32_16x16x32_bf16 v[48:51], v[196:199], v[154:157], v[48:51]
	v_mfma_f32_16x16x32_bf16 v[44:47], v[204:207], v[154:157], v[44:47]
	v_mfma_f32_16x16x32_bf16 v[32:35], v[196:199], v[172:175], v[32:35]
	v_mfma_f32_16x16x32_bf16 v[28:31], v[204:207], v[172:175], v[28:31]
	v_mfma_f32_16x16x32_bf16 v[16:19], v[196:199], v[180:183], v[16:19]
	v_mfma_f32_16x16x32_bf16 v[12:15], v[204:207], v[180:183], v[12:15]
	v_mfma_f32_16x16x32_bf16 v[4:7], v[196:199], v[188:191], v[4:7]
	v_mfma_f32_16x16x32_bf16 v[0:3], v[204:207], v[188:191], v[0:3]
	v_mfma_f32_16x16x32_bf16 v[48:51], v[200:203], v[162:165], v[48:51]
	v_mfma_f32_16x16x32_bf16 v[44:47], v[212:215], v[162:165], v[44:47]
	v_mfma_f32_16x16x32_bf16 v[32:35], v[200:203], v[176:179], v[32:35]
	v_mfma_f32_16x16x32_bf16 v[28:31], v[212:215], v[176:179], v[28:31]
	v_mfma_f32_16x16x32_bf16 v[16:19], v[200:203], v[184:187], v[16:19]
	v_mfma_f32_16x16x32_bf16 v[12:15], v[212:215], v[184:187], v[12:15]
	v_mfma_f32_16x16x32_bf16 v[4:7], v[200:203], v[192:195], v[4:7]
	v_mfma_f32_16x16x32_bf16 v[0:3], v[212:215], v[192:195], v[0:3]

	s_add_i32 s55, 0, 0x18000

	s_barrier
	ds_read_b128 v[128:131], v159 offset:32768
	ds_read_b128 v[132:135], v159 offset:33792
	ds_read_b128 v[136:139], v159 offset:34816
	ds_read_b128 v[150:153], v159 offset:35840
	s_add_u32 s20, s20, 0x160000
	s_addc_u32 s21, s21, 0
	s_mov_b32 m0, s28

	ds_read_b128 v[154:157], v160 offset:32768
	ds_read_b128 v[162:165], v160 offset:33792
	ds_read_b128 v[172:175], v160 offset:34816
	ds_read_b128 v[176:179], v160 offset:35840
	ds_read_b128 v[180:183], v160 offset:36864
	ds_read_b128 v[184:187], v160 offset:37888
	ds_read_b128 v[188:191], v160 offset:38912
	ds_read_b128 v[192:195], v160 offset:39936
	global_load_lds_dwordx4 v140, s[20:21]
	s_mov_b32 m0, s29
	s_nop 0

	global_load_lds_dwordx4 v142, s[20:21]
	s_waitcnt lgkmcnt(8)
	s_barrier
	s_waitcnt lgkmcnt(0)


	v_mfma_f32_16x16x32_bf16 v[124:127], v[128:131], v[154:157], v[124:127]
	v_mfma_f32_16x16x32_bf16 v[120:123], v[136:139], v[154:157], v[120:123]
	v_mfma_f32_16x16x32_bf16 v[116:119], v[128:131], v[172:175], v[116:119]
	v_mfma_f32_16x16x32_bf16 v[104:107], v[136:139], v[172:175], v[104:107]
	v_mfma_f32_16x16x32_bf16 v[96:99], v[128:131], v[180:183], v[96:99]
	v_mfma_f32_16x16x32_bf16 v[88:91], v[136:139], v[180:183], v[88:91]
	v_mfma_f32_16x16x32_bf16 v[80:83], v[128:131], v[188:191], v[80:83]
	v_mfma_f32_16x16x32_bf16 v[72:75], v[136:139], v[188:191], v[72:75]
	v_mfma_f32_16x16x32_bf16 v[124:127], v[132:135], v[162:165], v[124:127]
	v_mfma_f32_16x16x32_bf16 v[120:123], v[150:153], v[162:165], v[120:123]
	v_mfma_f32_16x16x32_bf16 v[116:119], v[132:135], v[176:179], v[116:119]
	v_mfma_f32_16x16x32_bf16 v[104:107], v[150:153], v[176:179], v[104:107]
	v_mfma_f32_16x16x32_bf16 v[96:99], v[132:135], v[184:187], v[96:99]
	v_mfma_f32_16x16x32_bf16 v[88:91], v[150:153], v[184:187], v[88:91]
	v_mfma_f32_16x16x32_bf16 v[80:83], v[132:135], v[192:195], v[80:83]
	v_mfma_f32_16x16x32_bf16 v[72:75], v[150:153], v[192:195], v[72:75]

	s_barrier
	s_add_i32 s20, 0, 0x1c000
	s_add_i32 s21, s55, s25


	s_mov_b32 m0, s21
	ds_read_b128 v[196:199], v161 offset:32768
	ds_read_b128 v[200:203], v161 offset:33792
	ds_read_b128 v[204:207], v161 offset:34816
	ds_read_b128 v[212:215], v161 offset:35840
	global_load_lds_dwordx4 v140, s[66:67]
	s_add_i32 m0, s21, 0x2000
	s_nop 0

	global_load_lds_dwordx4 v142, s[66:67]
	s_barrier
	s_waitcnt lgkmcnt(0)


	v_mfma_f32_16x16x32_bf16 v[112:115], v[196:199], v[154:157], v[112:115]
	v_mfma_f32_16x16x32_bf16 v[108:111], v[204:207], v[154:157], v[108:111]
	v_mfma_f32_16x16x32_bf16 v[100:103], v[196:199], v[172:175], v[100:103]
	v_mfma_f32_16x16x32_bf16 v[92:95], v[204:207], v[172:175], v[92:95]
	v_mfma_f32_16x16x32_bf16 v[84:87], v[196:199], v[180:183], v[84:87]
	v_mfma_f32_16x16x32_bf16 v[76:79], v[204:207], v[180:183], v[76:79]
	v_mfma_f32_16x16x32_bf16 v[68:71], v[196:199], v[188:191], v[68:71]
	v_mfma_f32_16x16x32_bf16 v[64:67], v[204:207], v[188:191], v[64:67]
	v_mfma_f32_16x16x32_bf16 v[112:115], v[200:203], v[162:165], v[112:115]
	v_mfma_f32_16x16x32_bf16 v[108:111], v[212:215], v[162:165], v[108:111]
	v_mfma_f32_16x16x32_bf16 v[100:103], v[200:203], v[176:179], v[100:103]
	v_mfma_f32_16x16x32_bf16 v[92:95], v[212:215], v[176:179], v[92:95]
	v_mfma_f32_16x16x32_bf16 v[84:87], v[200:203], v[184:187], v[84:87]
	v_mfma_f32_16x16x32_bf16 v[76:79], v[212:215], v[184:187], v[76:79]
	v_mfma_f32_16x16x32_bf16 v[68:71], v[200:203], v[192:195], v[68:71]
	v_mfma_f32_16x16x32_bf16 v[64:67], v[212:215], v[192:195], v[64:67]

	s_mov_b32 m0, s33

	s_barrier
	ds_read_b128 v[154:157], v160 offset:49152
	ds_read_b128 v[162:165], v160 offset:50176
	ds_read_b128 v[172:175], v160 offset:51200
	ds_read_b128 v[176:179], v160 offset:52224
	ds_read_b128 v[180:183], v160 offset:53248
	ds_read_b128 v[184:187], v160 offset:54272
	ds_read_b128 v[188:191], v160 offset:55296
	ds_read_b128 v[192:195], v160 offset:56320
	global_load_lds_dwordx4 v140, s[68:69]
	s_mov_b32 m0, s34
	s_nop 0

	global_load_lds_dwordx4 v142, s[68:69]
	s_barrier
	s_waitcnt lgkmcnt(0)


	v_mfma_f32_16x16x32_bf16 v[60:63], v[128:131], v[154:157], v[60:63]
	v_mfma_f32_16x16x32_bf16 v[56:59], v[136:139], v[154:157], v[56:59]
	v_mfma_f32_16x16x32_bf16 v[52:55], v[128:131], v[172:175], v[52:55]
	v_mfma_f32_16x16x32_bf16 v[40:43], v[136:139], v[172:175], v[40:43]
	v_mfma_f32_16x16x32_bf16 v[36:39], v[128:131], v[180:183], v[36:39]
	v_mfma_f32_16x16x32_bf16 v[24:27], v[136:139], v[180:183], v[24:27]
	v_mfma_f32_16x16x32_bf16 v[20:23], v[128:131], v[188:191], v[20:23]
	v_mfma_f32_16x16x32_bf16 v[8:11], v[136:139], v[188:191], v[8:11]
	v_mfma_f32_16x16x32_bf16 v[60:63], v[132:135], v[162:165], v[60:63]
	v_mfma_f32_16x16x32_bf16 v[56:59], v[150:153], v[162:165], v[56:59]
	v_mfma_f32_16x16x32_bf16 v[52:55], v[132:135], v[176:179], v[52:55]
	v_mfma_f32_16x16x32_bf16 v[40:43], v[150:153], v[176:179], v[40:43]
	v_mfma_f32_16x16x32_bf16 v[36:39], v[132:135], v[184:187], v[36:39]
	v_mfma_f32_16x16x32_bf16 v[24:27], v[150:153], v[184:187], v[24:27]
	v_mfma_f32_16x16x32_bf16 v[20:23], v[132:135], v[192:195], v[20:23]
	v_mfma_f32_16x16x32_bf16 v[8:11], v[150:153], v[192:195], v[8:11]

	s_barrier
	s_add_u32 s18, s18, 0x160080
	s_addc_u32 s19, s19, 0
	s_add_i32 s20, s20, s25
	s_mov_b32 m0, s20
	s_add_u32 s16, s16, 0x100
	s_addc_u32 s17, s17, 0

	global_load_lds_dwordx4 v140, s[18:19]
	s_add_i32 m0, s20, 0x2000
	s_add_u32 s52, s52, 0x100
	s_addc_u32 s53, s53, 0

	global_load_lds_dwordx4 v142, s[18:19]
	s_waitcnt vmcnt(6)
	s_barrier

	v_mfma_f32_16x16x32_bf16 v[48:51], v[196:199], v[154:157], v[48:51]
	v_mfma_f32_16x16x32_bf16 v[44:47], v[204:207], v[154:157], v[44:47]
	v_mfma_f32_16x16x32_bf16 v[32:35], v[196:199], v[172:175], v[32:35]
	v_mfma_f32_16x16x32_bf16 v[28:31], v[204:207], v[172:175], v[28:31]
	v_mfma_f32_16x16x32_bf16 v[16:19], v[196:199], v[180:183], v[16:19]
	v_mfma_f32_16x16x32_bf16 v[12:15], v[204:207], v[180:183], v[12:15]
	v_mfma_f32_16x16x32_bf16 v[4:7], v[196:199], v[188:191], v[4:7]
	v_mfma_f32_16x16x32_bf16 v[0:3], v[204:207], v[188:191], v[0:3]
	v_mfma_f32_16x16x32_bf16 v[48:51], v[200:203], v[162:165], v[48:51]
	v_mfma_f32_16x16x32_bf16 v[44:47], v[212:215], v[162:165], v[44:47]
	v_mfma_f32_16x16x32_bf16 v[32:35], v[200:203], v[176:179], v[32:35]
	v_mfma_f32_16x16x32_bf16 v[28:31], v[212:215], v[176:179], v[28:31]
	v_mfma_f32_16x16x32_bf16 v[16:19], v[200:203], v[184:187], v[16:19]
	v_mfma_f32_16x16x32_bf16 v[12:15], v[212:215], v[184:187], v[12:15]
	v_mfma_f32_16x16x32_bf16 v[4:7], v[200:203], v[192:195], v[4:7]
	v_mfma_f32_16x16x32_bf16 v[0:3], v[212:215], v[192:195], v[0:3]


	s_cmp_ge_i32 s54, s51
	s_mov_b32 s18, s54
	s_barrier
	s_cbranch_scc0 .LBB0_1258
	v_mov_b32_e32 v128, v210
	v_mov_b32_e32 v129, v169
	s_mov_b64 s[16:17], -1
	v_lshl_add_u32 v128, v128, 4, v129
	v_ashrrev_i32_e32 v150, 2, v128
	v_and_b32_e32 v129, 3, v129
	v_and_b32_e32 v128, -4, v128
	v_lshl_add_u32 v162, v129, 6, v128
	s_cmp_lt_i32 s2, 0
	v_lshlrev_b32_e32 v144, 4, v129
	s_cbranch_scc0 .LBB0_1261
	s_lshl_b32 s13, s50, 8
	s_add_i32 s13, s13, s30
	v_add_u32_e32 v128, s13, v150
	v_ashrrev_i32_e32 v129, 31, v128
	v_readlane_b32 s52, v254, 22
	v_lshlrev_b64 v[128:129], 13, v[128:129]
	v_readlane_b32 s66, v254, 36
	v_readlane_b32 s67, v254, 37
	s_lshl_b32 s16, s49, 8
	s_ashr_i32 s17, s16, 31
	v_lshl_add_u64 v[128:129], s[66:67], 0, v[128:129]
	v_lshl_add_u64 v[128:129], s[16:17], 2, v[128:129]
	s_lshl_b32 s16, s31, 2
	s_mov_b32 s17, s3
	v_lshl_add_u64 v[128:129], v[128:129], 0, s[16:17]
	v_lshl_add_u64 v[152:153], v[128:129], 0, v[144:145]
	global_load_dwordx4 v[164:167], v[152:153], off
	global_load_dwordx4 v[172:175], v[152:153], off offset:64
	global_load_dwordx4 v[176:179], v[152:153], off offset:512
	global_load_dwordx4 v[180:183], v[152:153], off offset:576
	v_add_co_u32_e32 v136, vcc, s37, v152
	ds_bpermute_b32 v138, v162, v124
	s_nop 0
	v_addc_co_u32_e32 v137, vcc, 0, v153, vcc
	global_load_dwordx4 v[184:187], v[136:137], off
	global_load_dwordx4 v[188:191], v[136:137], off offset:64
	global_load_dwordx4 v[192:195], v[136:137], off offset:512
	global_load_dwordx4 v[132:135], v[136:137], off offset:576
	v_add_co_u32_e32 v208, vcc, s38, v152
	ds_bpermute_b32 v139, v162, v125
	s_nop 0
	v_addc_co_u32_e32 v209, vcc, 0, v153, vcc
	global_load_dwordx4 v[196:199], v[208:209], off
	global_load_dwordx4 v[200:203], v[208:209], off offset:64
	global_load_dwordx4 v[204:207], v[208:209], off offset:512
	global_load_dwordx4 v[212:215], v[208:209], off offset:576
	v_add_co_u32_e32 v154, vcc, s39, v152
	ds_bpermute_b32 v156, v162, v126
	s_nop 0
	v_addc_co_u32_e32 v155, vcc, 0, v153, vcc
	global_load_dwordx4 v[216:219], v[154:155], off
	global_load_dwordx4 v[220:223], v[154:155], off offset:64
	global_load_dwordx4 v[224:227], v[154:155], off offset:512
	global_load_dwordx4 v[128:131], v[154:155], off offset:576
	ds_bpermute_b32 v157, v162, v127
	ds_bpermute_b32 v228, v162, v120
	ds_bpermute_b32 v229, v162, v121
	ds_bpermute_b32 v230, v162, v122
	ds_bpermute_b32 v231, v162, v123
	ds_bpermute_b32 v232, v162, v112
	ds_bpermute_b32 v233, v162, v113
	ds_bpermute_b32 v234, v162, v114
	ds_bpermute_b32 v235, v162, v115
	ds_bpermute_b32 v236, v162, v108
	ds_bpermute_b32 v237, v162, v109
	ds_bpermute_b32 v238, v162, v110
	ds_bpermute_b32 v239, v162, v111
	ds_bpermute_b32 v240, v162, v116
	ds_bpermute_b32 v241, v162, v117
	ds_bpermute_b32 v242, v162, v118
	ds_bpermute_b32 v243, v162, v119
	ds_bpermute_b32 v244, v162, v104
	ds_bpermute_b32 v245, v162, v105
	ds_bpermute_b32 v246, v162, v106
	ds_bpermute_b32 v247, v162, v107
	ds_bpermute_b32 v248, v162, v100
	ds_bpermute_b32 v249, v162, v101
	ds_bpermute_b32 v250, v162, v102
	ds_bpermute_b32 v251, v162, v103
	ds_bpermute_b32 v252, v162, v94
	ds_bpermute_b32 v253, v162, v95
	v_readlane_b32 s53, v254, 23
	v_readlane_b32 s54, v254, 24
	v_readlane_b32 s55, v254, 25
	v_readlane_b32 s56, v254, 26
	v_readlane_b32 s57, v254, 27
	v_readlane_b32 s58, v254, 28
	v_readlane_b32 s59, v254, 29
	v_readlane_b32 s60, v254, 30
	v_readlane_b32 s61, v254, 31
	v_readlane_b32 s62, v254, 32
	v_readlane_b32 s63, v254, 33
	v_readlane_b32 s64, v254, 34
	v_readlane_b32 s65, v254, 35
	s_mov_b64 s[16:17], 0
	s_waitcnt vmcnt(0) lgkmcnt(0)
	v_pk_add_f32 v[164:165], v[164:165], v[138:139]
	ds_bpermute_b32 v138, v162, v92
	ds_bpermute_b32 v139, v162, v93
	v_pk_add_f32 v[166:167], v[166:167], v[156:157]
	v_pk_add_f32 v[172:173], v[172:173], v[228:229]
	v_pk_add_f32 v[174:175], v[174:175], v[230:231]
	v_pk_add_f32 v[178:179], v[178:179], v[234:235]
	v_pk_add_f32 v[176:177], v[176:177], v[232:233]
	v_pk_add_f32 v[182:183], v[182:183], v[238:239]
	v_pk_add_f32 v[180:181], v[180:181], v[236:237]
	global_store_dwordx4 v[152:153], v[164:167], off
	global_store_dwordx4 v[152:153], v[172:175], off offset:64
	global_store_dwordx4 v[152:153], v[176:179], off offset:512
	global_store_dwordx4 v[152:153], v[180:183], off offset:576
	v_pk_add_f32 v[166:167], v[186:187], v[242:243]
	v_pk_add_f32 v[164:165], v[184:185], v[240:241]
	v_pk_add_f32 v[172:173], v[188:189], v[244:245]
	v_add_co_u32_e32 v156, vcc, s40, v152
	v_pk_add_f32 v[174:175], v[190:191], v[246:247]
	v_pk_add_f32 v[178:179], v[194:195], v[250:251]
	v_pk_add_f32 v[176:177], v[192:193], v[248:249]
	global_store_dwordx4 v[136:137], v[164:167], off
	global_store_dwordx4 v[136:137], v[172:175], off offset:64
	global_store_dwordx4 v[136:137], v[176:179], off offset:512
	v_addc_co_u32_e32 v157, vcc, 0, v153, vcc
	ds_bpermute_b32 v172, v162, v98
	ds_bpermute_b32 v173, v162, v99
	v_pk_add_f32 v[134:135], v[134:135], v[252:253]
	global_load_dwordx4 v[164:167], v[156:157], off
	s_waitcnt lgkmcnt(2)
	v_pk_add_f32 v[132:133], v[132:133], v[138:139]
	global_store_dwordx4 v[136:137], v[132:135], off offset:576
	ds_bpermute_b32 v132, v162, v96
	ds_bpermute_b32 v133, v162, v97
	ds_bpermute_b32 v136, v162, v90
	ds_bpermute_b32 v137, v162, v91
	ds_bpermute_b32 v138, v162, v88
	ds_bpermute_b32 v139, v162, v89
	s_waitcnt lgkmcnt(6)
	v_pk_add_f32 v[134:135], v[198:199], v[172:173]
	global_load_dwordx4 v[172:175], v[156:157], off offset:64
	s_waitcnt lgkmcnt(4)
	v_pk_add_f32 v[132:133], v[196:197], v[132:133]
	global_store_dwordx4 v[208:209], v[132:135], off
	ds_bpermute_b32 v180, v162, v76
	ds_bpermute_b32 v182, v162, v78
	s_waitcnt lgkmcnt(4)
	v_pk_add_f32 v[134:135], v[202:203], v[136:137]
	ds_bpermute_b32 v136, v162, v86
	ds_bpermute_b32 v137, v162, v87
	s_waitcnt lgkmcnt(4)
	v_pk_add_f32 v[132:133], v[200:201], v[138:139]
	ds_bpermute_b32 v138, v162, v84
	ds_bpermute_b32 v139, v162, v85
	global_store_dwordx4 v[208:209], v[132:135], off offset:64
	global_load_dwordx4 v[132:135], v[156:157], off offset:512
	s_waitcnt lgkmcnt(2)
	v_pk_add_f32 v[178:179], v[206:207], v[136:137]
	ds_bpermute_b32 v183, v162, v79
	s_waitcnt lgkmcnt(1)
	v_pk_add_f32 v[176:177], v[204:205], v[138:139]
	global_load_dwordx4 v[136:139], v[156:157], off offset:576
	ds_bpermute_b32 v181, v162, v77
	global_store_dwordx4 v[208:209], v[176:179], off offset:512
	v_add_co_u32_e32 v204, vcc, s41, v152
	s_waitcnt lgkmcnt(1)
	v_pk_add_f32 v[178:179], v[214:215], v[182:183]
	s_waitcnt lgkmcnt(0)
	v_pk_add_f32 v[176:177], v[212:213], v[180:181]
	ds_bpermute_b32 v180, v162, v80
	ds_bpermute_b32 v181, v162, v81
	ds_bpermute_b32 v182, v162, v82
	ds_bpermute_b32 v183, v162, v83
	v_addc_co_u32_e32 v205, vcc, 0, v153, vcc
	global_store_dwordx4 v[208:209], v[176:179], off offset:576
	global_load_dwordx4 v[176:179], v[204:205], off
	s_waitcnt lgkmcnt(0)
	v_pk_add_f32 v[182:183], v[218:219], v[182:183]
	global_load_dwordx4 v[184:187], v[204:205], off offset:64
	v_pk_add_f32 v[180:181], v[216:217], v[180:181]
	ds_bpermute_b32 v188, v162, v74
	ds_bpermute_b32 v189, v162, v75
	global_store_dwordx4 v[154:155], v[180:183], off
	ds_bpermute_b32 v180, v162, v72
	ds_bpermute_b32 v181, v162, v73
	ds_bpermute_b32 v192, v162, v68
	s_waitcnt lgkmcnt(3)
	v_pk_add_f32 v[182:183], v[222:223], v[188:189]
	global_load_dwordx4 v[188:191], v[204:205], off offset:512
	ds_bpermute_b32 v193, v162, v69
	s_waitcnt lgkmcnt(2)
	v_pk_add_f32 v[180:181], v[220:221], v[180:181]
	ds_bpermute_b32 v194, v162, v70
	ds_bpermute_b32 v195, v162, v71
	global_store_dwordx4 v[154:155], v[180:183], off offset:64
	global_load_dwordx4 v[180:183], v[204:205], off offset:576
	ds_bpermute_b32 v200, v162, v64
	ds_bpermute_b32 v196, v162, v66
	ds_bpermute_b32 v197, v162, v67
	ds_bpermute_b32 v201, v162, v65
	v_add_co_u32_e32 v206, vcc, s42, v152
	s_waitcnt lgkmcnt(4)
	v_pk_add_f32 v[194:195], v[226:227], v[194:195]
	v_pk_add_f32 v[192:193], v[224:225], v[192:193]
	v_addc_co_u32_e32 v207, vcc, 0, v153, vcc
	global_store_dwordx4 v[154:155], v[192:195], off offset:512
	global_load_dwordx4 v[192:195], v[206:207], off
	s_waitcnt lgkmcnt(1)
	v_pk_add_f32 v[130:131], v[130:131], v[196:197]
	s_waitcnt lgkmcnt(0)
	v_pk_add_f32 v[128:129], v[128:129], v[200:201]
	global_load_dwordx4 v[196:199], v[206:207], off offset:64
	ds_bpermute_b32 v202, v162, v62
	ds_bpermute_b32 v203, v162, v63
	global_store_dwordx4 v[154:155], v[128:131], off offset:576
	ds_bpermute_b32 v128, v162, v60
	ds_bpermute_b32 v129, v162, v61
	ds_bpermute_b32 v208, v162, v58
	ds_bpermute_b32 v209, v162, v59
	s_waitcnt vmcnt(18) lgkmcnt(4)
	v_pk_add_f32 v[130:131], v[166:167], v[202:203]
	ds_bpermute_b32 v154, v162, v56
	global_load_dwordx4 v[200:203], v[206:207], off offset:512
	ds_bpermute_b32 v155, v162, v57
	s_waitcnt lgkmcnt(4)
	v_pk_add_f32 v[128:129], v[164:165], v[128:129]
	global_load_dwordx4 v[164:167], v[206:207], off offset:576
	ds_bpermute_b32 v212, v162, v44
	global_store_dwordx4 v[156:157], v[128:131], off
	ds_bpermute_b32 v214, v162, v46
	ds_bpermute_b32 v215, v162, v47
	s_waitcnt vmcnt(19) lgkmcnt(5)
	v_pk_add_f32 v[130:131], v[174:175], v[208:209]
	v_add_co_u32_e32 v208, vcc, s43, v152
	s_waitcnt lgkmcnt(3)
	v_pk_add_f32 v[128:129], v[172:173], v[154:155]
	v_addc_co_u32_e32 v209, vcc, 0, v153, vcc
	global_store_dwordx4 v[156:157], v[128:131], off offset:64
	ds_bpermute_b32 v172, v162, v48
	ds_bpermute_b32 v173, v162, v49
	global_load_dwordx4 v[128:131], v[208:209], off
	global_load_dwordx4 v[152:155], v[208:209], off offset:64
	ds_bpermute_b32 v174, v162, v50
	ds_bpermute_b32 v175, v162, v51
	ds_bpermute_b32 v213, v162, v45
	s_waitcnt vmcnt(19) lgkmcnt(3)
	v_pk_add_f32 v[132:133], v[132:133], v[172:173]
	ds_bpermute_b32 v172, v162, v54
	ds_bpermute_b32 v173, v162, v55
	s_waitcnt lgkmcnt(3)
	v_pk_add_f32 v[134:135], v[134:135], v[174:175]
	global_store_dwordx4 v[156:157], v[132:135], off offset:512
	s_waitcnt vmcnt(16) lgkmcnt(0)
	v_pk_add_f32 v[174:175], v[178:179], v[172:173]
	v_pk_add_f32 v[134:135], v[138:139], v[214:215]
	v_pk_add_f32 v[132:133], v[136:137], v[212:213]
	global_store_dwordx4 v[156:157], v[132:135], off offset:576
	global_load_dwordx4 v[132:135], v[208:209], off offset:512
	ds_bpermute_b32 v156, v162, v52
	global_load_dwordx4 v[136:139], v[208:209], off offset:576
	ds_bpermute_b32 v157, v162, v53
	ds_bpermute_b32 v212, v162, v40
	ds_bpermute_b32 v214, v162, v42
	ds_bpermute_b32 v215, v162, v43
	ds_bpermute_b32 v213, v162, v41
	s_waitcnt lgkmcnt(4)
	v_pk_add_f32 v[172:173], v[176:177], v[156:157]
	global_store_dwordx4 v[204:205], v[172:175], off
	ds_bpermute_b32 v156, v162, v32
	ds_bpermute_b32 v157, v162, v33
	s_waitcnt vmcnt(19) lgkmcnt(3)
	v_pk_add_f32 v[174:175], v[186:187], v[214:215]
	s_waitcnt lgkmcnt(2)
	v_pk_add_f32 v[172:173], v[184:185], v[212:213]
	global_store_dwordx4 v[204:205], v[172:175], off offset:64
	ds_bpermute_b32 v172, v162, v34
	ds_bpermute_b32 v173, v162, v35
	ds_bpermute_b32 v176, v162, v28
	ds_bpermute_b32 v178, v162, v30
	ds_bpermute_b32 v179, v162, v31
	ds_bpermute_b32 v177, v162, v29
	s_waitcnt vmcnt(18) lgkmcnt(4)
	v_pk_add_f32 v[174:175], v[190:191], v[172:173]
	v_pk_add_f32 v[172:173], v[188:189], v[156:157]
	global_store_dwordx4 v[204:205], v[172:175], off offset:512
	ds_bpermute_b32 v156, v162, v36
	ds_bpermute_b32 v157, v162, v37
	s_waitcnt vmcnt(17) lgkmcnt(3)
	v_pk_add_f32 v[174:175], v[182:183], v[178:179]
	s_waitcnt lgkmcnt(2)
	v_pk_add_f32 v[172:173], v[180:181], v[176:177]
	global_store_dwordx4 v[204:205], v[172:175], off offset:576
	ds_bpermute_b32 v172, v162, v38
	ds_bpermute_b32 v173, v162, v39
	ds_bpermute_b32 v176, v162, v24
	ds_bpermute_b32 v178, v162, v26
	ds_bpermute_b32 v179, v162, v27
	ds_bpermute_b32 v177, v162, v25
	s_waitcnt vmcnt(16) lgkmcnt(4)
	v_pk_add_f32 v[174:175], v[194:195], v[172:173]
	v_pk_add_f32 v[172:173], v[192:193], v[156:157]
	global_store_dwordx4 v[206:207], v[172:175], off
	ds_bpermute_b32 v156, v162, v16
	ds_bpermute_b32 v157, v162, v17
	s_waitcnt vmcnt(16) lgkmcnt(3)
	v_pk_add_f32 v[174:175], v[198:199], v[178:179]
	s_waitcnt lgkmcnt(2)
	v_pk_add_f32 v[172:173], v[196:197], v[176:177]
	ds_bpermute_b32 v176, v162, v12
	ds_bpermute_b32 v178, v162, v14
	ds_bpermute_b32 v179, v162, v15
	ds_bpermute_b32 v177, v162, v13
	global_store_dwordx4 v[206:207], v[172:175], off offset:64
	ds_bpermute_b32 v172, v162, v18
	ds_bpermute_b32 v173, v162, v19
	s_waitcnt vmcnt(14) lgkmcnt(3)
	v_pk_add_f32 v[166:167], v[166:167], v[178:179]
	s_waitcnt lgkmcnt(2)
	v_pk_add_f32 v[164:165], v[164:165], v[176:177]
	global_store_dwordx4 v[206:207], v[164:167], off offset:576
	ds_bpermute_b32 v164, v162, v22
	s_waitcnt lgkmcnt(1)
	v_pk_add_f32 v[174:175], v[202:203], v[172:173]
	v_pk_add_f32 v[172:173], v[200:201], v[156:157]
	ds_bpermute_b32 v156, v162, v20
	ds_bpermute_b32 v157, v162, v21
	ds_bpermute_b32 v165, v162, v23
	global_store_dwordx4 v[206:207], v[172:175], off offset:512
	ds_bpermute_b32 v166, v162, v8
	ds_bpermute_b32 v172, v162, v10
	ds_bpermute_b32 v173, v162, v11
	ds_bpermute_b32 v167, v162, v9
	s_waitcnt vmcnt(13) lgkmcnt(4)
	v_pk_add_f32 v[130:131], v[130:131], v[164:165]
	v_pk_add_f32 v[128:129], v[128:129], v[156:157]
	global_store_dwordx4 v[208:209], v[128:131], off
	s_waitcnt vmcnt(13) lgkmcnt(1)
	s_nop 0
	v_pk_add_f32 v[130:131], v[154:155], v[172:173]
	s_waitcnt lgkmcnt(0)
	v_pk_add_f32 v[128:129], v[152:153], v[166:167]
	global_store_dwordx4 v[208:209], v[128:131], off offset:64
	ds_bpermute_b32 v128, v162, v4
	ds_bpermute_b32 v129, v162, v5
	ds_bpermute_b32 v130, v162, v6
	ds_bpermute_b32 v131, v162, v7
	ds_bpermute_b32 v152, v162, v0
	ds_bpermute_b32 v154, v162, v2
	ds_bpermute_b32 v155, v162, v3
	ds_bpermute_b32 v153, v162, v1
	s_waitcnt vmcnt(11) lgkmcnt(4)
	v_pk_add_f32 v[130:131], v[134:135], v[130:131]
	v_pk_add_f32 v[128:129], v[132:133], v[128:129]
	global_store_dwordx4 v[208:209], v[128:131], off offset:512
	s_waitcnt vmcnt(11) lgkmcnt(1)
	s_nop 0
	v_pk_add_f32 v[130:131], v[138:139], v[154:155]
	s_waitcnt lgkmcnt(0)
	v_pk_add_f32 v[128:129], v[136:137], v[152:153]
	global_store_dwordx4 v[208:209], v[128:131], off offset:576
